# prestage of big-tile K-tile 0 after the grid barrier also in P5, P9, P12 (split-K LDS buffer relocated)
# speedup vs baseline: 1.0228x; 1.0056x over previous
.LBB0_768:
	s_or_b64 exec, exec, s[0:1]
	s_cmpk_lt_i32 s2, 0x100
	v_bfe_u32 v183, v136, 1, 2
	s_movk_i32 s0, 0x100
	s_cselect_b64 s[10:11], -1, 0
	s_cmpk_gt_i32 s2, 0xff
	v_lshrrev_b32_e32 v187, 6, v136
	v_lshlrev_b32_e32 v190, 11, v136
	v_lshrrev_b32_e32 v252, 1, v136
	v_and_b32_e32 v132, 48, v136
	v_and_b32_e32 v189, 63, v136
	v_lshrrev_b32_e32 v182, 3, v136
	v_lshlrev_b32_e32 v188, 2, v136
	v_lshl_add_u32 v186, v183, 6, 0
	s_waitcnt lgkmcnt(0)
	s_barrier
	v_lshlrev_b32_e32 v150, 4, v136
	v_and_b32_e32 v151, 0x3ff, v150
	v_lshrrev_b32_e32 v152, 4, v151
	v_and_b32_e32 v152, 32, v152
	v_xor_b32_e32 v151, v151, v152
	v_lshrrev_b32_e32 v152, 10, v150
	v_lshrrev_b32_e32 v153, 1, v152
	v_lshlrev_b32_e32 v153, 4, v153
	v_lshrrev_b32_e32 v150, 6, v151
	v_add_u32_e32 v153, v153, v150
	v_mul_u32_u24_e32 v153, 0x800, v153
	v_and_b32_e32 v152, 1, v152
	v_lshl_add_u32 v153, v152, 6, v153
	v_and_b32_e32 v151, 63, v151
	v_add_u32_e32 v150, v153, v151
	v_add_u32_e32 v151, 0x20000, v150
	s_and_b32 s72, s2, 7
	s_lshl_b32 s72, s72, 3
	s_bfe_u32 s73, s2, 0x30003
	s_or_b32 s72, s72, s73
	s_mul_i32 s72, s72, 0x80000
	s_add_u32 s74, s56, s72
	s_addc_u32 s75, s57, 0
	v_readlane_b32 s76, v253, 63
	v_readlane_b32 s77, v254, 0
	s_lshr_b32 s72, s2, 6
	s_mul_i32 s72, s72, 0x80000
	s_nop 0
	s_add_u32 s76, s76, s72
	s_addc_u32 s77, s77, 0
	s_add_u32 s78, s76, 0x40000
	s_addc_u32 s79, s77, 0
	s_add_u32 s80, s74, 0x40000
	s_addc_u32 s81, s75, 0
	v_readfirstlane_b32 s82, v136
	s_nop 0
	s_lshr_b32 s82, s82, 6
	s_lshl_b32 s82, s82, 10
	s_add_i32 m0, s82, 0x10000
	s_nop 0
	global_load_lds_dwordx4 v150, s[76:77]
	s_add_i32 m0, s82, 0x12000
	s_nop 0
	global_load_lds_dwordx4 v151, s[76:77]
	s_add_i32 m0, s82, 0x0
	s_nop 0
	global_load_lds_dwordx4 v150, s[74:75]
	s_add_i32 m0, s82, 0x2000
	s_nop 0
	global_load_lds_dwordx4 v151, s[74:75]
	s_add_i32 m0, s82, 0x14000
	s_nop 0
	global_load_lds_dwordx4 v150, s[78:79]
	s_add_i32 m0, s82, 0x16000
	s_nop 0
	global_load_lds_dwordx4 v151, s[78:79]
	s_add_i32 m0, s82, 0x4000
	s_nop 0
	global_load_lds_dwordx4 v150, s[80:81]
	s_add_i32 m0, s82, 0x6000
	s_nop 0
	global_load_lds_dwordx4 v151, s[80:81]
	s_cmpk_gt_i32 s2, 0xff
	s_cbranch_scc1 .LBB0_774
	v_readlane_b32 s12, v253, 51
	v_and_b32_e32 v0, 0x7800, v190
	v_mov_b32_e32 v1, 0
	v_readlane_b32 s24, v253, 63
	v_readlane_b32 s25, v254, 0
	v_mov_b32_e32 v133, v1
	v_and_b32_e32 v7, 4, v188
	v_lshl_add_u64 v[2:3], s[24:25], 0, v[0:1]
	v_lshl_add_u64 v[4:5], v[2:3], 0, v[132:133]
	v_lshl_add_u64 v[2:3], s[56:57], 0, v[0:1]
	v_and_or_b32 v6, v182, 16, v7
	v_lshl_add_u64 v[2:3], v[2:3], 0, v[132:133]
	v_lshlrev_b32_e32 v0, 8, v187
	v_and_b32_e32 v9, 60, v252
	v_lshlrev_b32_e32 v6, 8, v6
	v_readlane_b32 s14, v253, 53
	v_readlane_b32 s15, v253, 54
	v_readlane_b32 s16, v253, 55
	v_readlane_b32 s17, v253, 56
	v_readlane_b32 s18, v253, 57
	v_lshl_add_u64 v[2:3], v[2:3], 0, v[0:1]
	v_lshl_add_u64 v[4:5], v[4:5], 0, v[0:1]
	v_lshlrev_b32_e32 v0, 13, v187
	v_lshl_add_u32 v8, v189, 2, 0
	v_add3_u32 v6, v186, v9, v6
	v_and_b32_e32 v9, 7, v136
	s_mov_b32 s7, 0
	v_cmp_gt_u32_e32 vcc, s0, v136
	v_lshl_or_b32 v7, v183, 3, v7
	v_cmp_eq_u32_e64 s[0:1], 0, v9
	s_lshl_b32 s3, s2, 5
	s_lshl_b32 s14, s38, 5
	s_mov_b32 s15, 0x8000
	s_mov_b32 s16, 0x40000
	s_mov_b32 s17, 0x48000
	v_add_u32_e32 v8, v8, v0
	v_lshrrev_b32_e32 v185, 2, v187
	v_lshl_add_u32 v8, v185, 15, v8
	v_add_u32_e32 v8, 0x8000, v8
	v_add_u32_e32 v184, 0x10000, v6
	v_mbcnt_hi_u32_b32 v9, -1, v137
	s_mov_b32 s18, s2
	v_readlane_b32 s13, v253, 52
	v_readlane_b32 s19, v253, 58
	v_readlane_b32 s20, v253, 59
	v_readlane_b32 s21, v253, 60
	v_readlane_b32 s22, v253, 61
	v_readlane_b32 s23, v253, 62
	v_readlane_b32 s26, v254, 1
	v_readlane_b32 s27, v254, 2
	s_branch .LBB0_771

.LBB0_771:
	s_ashr_i32 s19, s18, 6
	s_bfe_u32 s20, s18, 0x20004
	s_lshl_b32 s4, s19, 8
	s_lshl_b32 s5, s20, 5
	s_or_b32 s8, s5, s4
	s_and_b32 s6, s3, 0x1e0
	s_ashr_i32 s9, s8, 31
	s_lshl_b64 s[4:5], s[8:9], 11
	s_or_b32 s9, s6, 0x4000
	s_lshl_b32 s6, s9, 11
	s_waitcnt vmcnt(33)
	v_lshl_add_u64 v[72:73], v[2:3], 0, s[6:7]
	v_lshl_add_u64 v[70:71], v[4:5], 0, s[4:5]
	v_add_co_u32_e64 v74, s[4:5], s15, v72
	s_waitcnt lgkmcnt(0)
	global_load_dwordx4 v[10:13], v[70:71], off
	v_addc_co_u32_e64 v75, s[4:5], 0, v73, s[4:5]
	v_add_co_u32_e64 v76, s[4:5], s15, v70
	global_load_dwordx4 v[14:17], v[72:73], off
	s_waitcnt vmcnt(34)
	v_addc_co_u32_e64 v77, s[4:5], 0, v71, s[4:5]
	v_add_co_u32_e64 v78, s[4:5], s16, v70
	global_load_dwordx4 v[18:21], v[72:73], off offset:64
	global_load_dwordx4 v[22:25], v[74:75], off
	v_addc_co_u32_e64 v79, s[4:5], 0, v71, s[4:5]
	v_add_co_u32_e64 v80, s[4:5], s17, v70
	global_load_dwordx4 v[26:29], v[70:71], off offset:64
	s_nop 0
	v_addc_co_u32_e64 v81, s[4:5], 0, v71, s[4:5]
	global_load_dwordx4 v[34:37], v[76:77], off
	global_load_dwordx4 v[38:41], v[74:75], off offset:64
	global_load_dwordx4 v[42:45], v[76:77], off offset:64
	global_load_dwordx4 v[50:53], v[78:79], off
	global_load_dwordx4 v[54:57], v[78:79], off offset:64
	global_load_dwordx4 v[62:65], v[80:81], off
	global_load_dwordx4 v[66:69], v[80:81], off offset:64
	s_waitcnt vmcnt(10)
	v_mfma_f32_16x16x32_bf16 v[30:33], v[10:13], v[14:17], 0
	s_waitcnt vmcnt(8)
	v_mfma_f32_16x16x32_bf16 v[10:13], v[10:13], v[22:25], 0
	s_waitcnt vmcnt(6)
	v_mfma_f32_16x16x32_bf16 v[46:49], v[34:37], v[14:17], 0
	v_mfma_f32_16x16x32_bf16 v[34:37], v[34:37], v[22:25], 0
	s_waitcnt vmcnt(3)
	v_mfma_f32_16x16x32_bf16 v[58:61], v[50:53], v[14:17], 0
	s_waitcnt vmcnt(1)
	v_mfma_f32_16x16x32_bf16 v[14:17], v[62:65], v[14:17], 0
	v_mfma_f32_16x16x32_bf16 v[30:33], v[26:29], v[18:21], v[30:33]
	v_mfma_f32_16x16x32_bf16 v[10:13], v[26:29], v[38:41], v[10:13]
	v_mfma_f32_16x16x32_bf16 v[26:29], v[42:45], v[18:21], v[46:49]
	v_mfma_f32_16x16x32_bf16 v[34:37], v[42:45], v[38:41], v[34:37]
	v_mfma_f32_16x16x32_bf16 v[42:45], v[54:57], v[18:21], v[58:61]
	s_waitcnt vmcnt(0)
	v_mfma_f32_16x16x32_bf16 v[14:17], v[66:69], v[18:21], v[14:17]
	global_load_dwordx4 v[18:21], v[70:71], off offset:128
	v_mfma_f32_16x16x32_bf16 v[50:53], v[50:53], v[22:25], 0
	v_mfma_f32_16x16x32_bf16 v[22:25], v[62:65], v[22:25], 0
	v_mfma_f32_16x16x32_bf16 v[46:49], v[54:57], v[38:41], v[50:53]
	v_mfma_f32_16x16x32_bf16 v[22:25], v[66:69], v[38:41], v[22:25]
	global_load_dwordx4 v[38:41], v[72:73], off offset:128
	s_nop 3
	global_load_dwordx4 v[50:53], v[72:73], off offset:192
	global_load_dwordx4 v[54:57], v[70:71], off offset:192
	global_load_dwordx4 v[58:61], v[74:75], off offset:128
	global_load_dwordx4 v[62:65], v[74:75], off offset:192
	s_waitcnt vmcnt(4)
	v_mfma_f32_16x16x32_bf16 v[30:33], v[18:21], v[38:41], v[30:33]
	s_waitcnt vmcnt(1)
	v_mfma_f32_16x16x32_bf16 v[10:13], v[18:21], v[58:61], v[10:13]
	global_load_dwordx4 v[18:21], v[76:77], off offset:128
	global_load_dwordx4 v[66:69], v[76:77], off offset:192
	v_mfma_f32_16x16x32_bf16 v[30:33], v[54:57], v[50:53], v[30:33]
	s_waitcnt vmcnt(2)
	v_mfma_f32_16x16x32_bf16 v[10:13], v[54:57], v[62:65], v[10:13]
	s_waitcnt vmcnt(1)
	v_mfma_f32_16x16x32_bf16 v[26:29], v[18:21], v[38:41], v[26:29]
	v_mfma_f32_16x16x32_bf16 v[18:21], v[18:21], v[58:61], v[34:37]
	s_nop 2
	global_load_dwordx4 v[34:37], v[78:79], off offset:128
	global_load_dwordx4 v[70:73], v[78:79], off offset:192
	global_load_dwordx4 v[74:77], v[80:81], off offset:128
	s_waitcnt vmcnt(3)
	v_mfma_f32_16x16x32_bf16 v[26:29], v[66:69], v[50:53], v[26:29]
	s_waitcnt vmcnt(2)
	v_mfma_f32_16x16x32_bf16 v[42:45], v[34:37], v[38:41], v[42:45]
	v_mfma_f32_16x16x32_bf16 v[34:37], v[34:37], v[58:61], v[46:49]
	s_nop 2
	global_load_dwordx4 v[46:49], v[80:81], off offset:192
	s_waitcnt vmcnt(1)
	v_mfma_f32_16x16x32_bf16 v[14:17], v[74:77], v[38:41], v[14:17]
	s_barrier
	ds_write2st64_b32 v8, v30, v31 offset1:1
	ds_write2st64_b32 v8, v32, v33 offset0:2 offset1:3
	v_mfma_f32_16x16x32_bf16 v[30:33], v[70:73], v[50:53], v[42:45]
	ds_write2st64_b32 v8, v26, v27 offset0:4 offset1:5
	ds_write2st64_b32 v8, v28, v29 offset0:6 offset1:7
	s_nop 5
	ds_write2st64_b32 v8, v30, v31 offset0:8 offset1:9
	v_mfma_f32_16x16x32_bf16 v[22:25], v[74:77], v[58:61], v[22:25]
	s_waitcnt vmcnt(0)
	v_mfma_f32_16x16x32_bf16 v[14:17], v[46:49], v[50:53], v[14:17]
	ds_write2st64_b32 v8, v32, v33 offset0:10 offset1:11
	s_nop 6
	ds_write2st64_b32 v8, v14, v15 offset0:12 offset1:13
	ds_write2st64_b32 v8, v16, v17 offset0:14 offset1:15
	v_mfma_f32_16x16x32_bf16 v[14:17], v[66:69], v[62:65], v[18:21]
	ds_write2st64_b32 v8, v10, v11 offset0:16 offset1:17
	ds_write2st64_b32 v8, v12, v13 offset0:18 offset1:19
	s_nop 5
	ds_write2st64_b32 v8, v14, v15 offset0:20 offset1:21
	v_mfma_f32_16x16x32_bf16 v[10:13], v[70:73], v[62:65], v[34:37]
	ds_write2st64_b32 v8, v16, v17 offset0:22 offset1:23
	s_nop 6
	ds_write2st64_b32 v8, v10, v11 offset0:24 offset1:25
	ds_write2st64_b32 v8, v12, v13 offset0:26 offset1:27
	v_mfma_f32_16x16x32_bf16 v[10:13], v[46:49], v[62:65], v[22:25]
	s_nop 7
	ds_write2st64_b32 v8, v10, v11 offset0:28 offset1:29
	ds_write2st64_b32 v8, v12, v13 offset0:30 offset1:31
	s_waitcnt lgkmcnt(0)
	s_barrier
	s_and_saveexec_b64 s[12:13], vcc
	s_cbranch_execz .LBB0_770
	ds_read2st64_b32 v[10:11], v6 offset0:128 offset1:129
	ds_read2st64_b32 v[12:13], v6 offset0:136 offset1:137
	ds_read2st64_b32 v[14:15], v6 offset0:138 offset1:139
	ds_read2st64_b32 v[16:17], v6 offset0:130 offset1:131
	s_waitcnt lgkmcnt(3)
	v_add_f32_e32 v0, 0, v10
	s_waitcnt lgkmcnt(2)
	v_add_f32_e32 v18, 0, v12
	v_add_f32_e32 v19, 0, v11
	v_add_f32_e32 v20, 0, v13
	ds_read2st64_b32 v[10:11], v6 offset0:160 offset1:161
	ds_read2st64_b32 v[12:13], v6 offset0:168 offset1:169
	s_waitcnt lgkmcnt(2)
	v_add_f32_e32 v21, 0, v16
	v_add_f32_e32 v22, 0, v14
	v_add_f32_e32 v23, 0, v17
	v_add_f32_e32 v24, 0, v15
	ds_read2st64_b32 v[14:15], v6 offset0:170 offset1:171
	ds_read2st64_b32 v[16:17], v6 offset0:162 offset1:163
	s_waitcnt lgkmcnt(3)
	v_add_f32_e32 v0, v0, v10
	s_waitcnt lgkmcnt(2)
	v_add_f32_e32 v18, v18, v12
	v_add_f32_e32 v19, v19, v11
	v_add_f32_e32 v20, v20, v13
	ds_read2st64_b32 v[10:11], v6 offset0:192 offset1:193
	ds_read2st64_b32 v[12:13], v6 offset0:200 offset1:201
	s_waitcnt lgkmcnt(2)
	v_add_f32_e32 v21, v21, v16
	v_add_f32_e32 v22, v22, v14
	v_add_f32_e32 v23, v23, v17
	v_add_f32_e32 v24, v24, v15
	ds_read2st64_b32 v[14:15], v6 offset0:202 offset1:203
	ds_read2st64_b32 v[16:17], v6 offset0:194 offset1:195
	s_waitcnt lgkmcnt(3)
	v_add_f32_e32 v0, v0, v10
	s_waitcnt lgkmcnt(2)
	v_add_f32_e32 v18, v18, v12
	v_add_f32_e32 v19, v19, v11
	v_add_f32_e32 v20, v20, v13
	ds_read2st64_b32 v[10:11], v6 offset0:224 offset1:225
	ds_read2st64_b32 v[12:13], v6 offset0:232 offset1:233
	s_waitcnt lgkmcnt(2)
	v_add_f32_e32 v21, v21, v16
	v_add_f32_e32 v22, v22, v14
	v_add_f32_e32 v23, v23, v17
	v_add_f32_e32 v24, v24, v15
	ds_read2st64_b32 v[14:15], v6 offset0:234 offset1:235
	ds_read2st64_b32 v[16:17], v6 offset0:226 offset1:227
	s_waitcnt lgkmcnt(3)
	v_add_f32_e32 v0, v0, v10
	s_waitcnt lgkmcnt(2)
	v_add_f32_e32 v18, v18, v12
	v_add_f32_e32 v19, v19, v11
	v_add_f32_e32 v20, v20, v13
	ds_read2st64_b32 v[10:11], v184 offset0:128 offset1:129
	ds_read2st64_b32 v[12:13], v184 offset0:136 offset1:137
	s_waitcnt lgkmcnt(2)
	v_add_f32_e32 v21, v21, v16
	v_add_f32_e32 v22, v22, v14
	v_add_f32_e32 v23, v23, v17
	v_add_f32_e32 v24, v24, v15
	ds_read2st64_b32 v[14:15], v184 offset0:138 offset1:139
	ds_read2st64_b32 v[16:17], v184 offset0:130 offset1:131
	s_waitcnt lgkmcnt(3)
	v_add_f32_e32 v0, v0, v10
	s_waitcnt lgkmcnt(2)
	v_add_f32_e32 v18, v18, v12
	v_add_f32_e32 v19, v19, v11
	v_add_f32_e32 v20, v20, v13
	ds_read2st64_b32 v[10:11], v184 offset0:160 offset1:161
	ds_read2st64_b32 v[12:13], v184 offset0:168 offset1:169
	s_waitcnt lgkmcnt(2)
	v_add_f32_e32 v21, v21, v16
	v_add_f32_e32 v22, v22, v14
	v_add_f32_e32 v23, v23, v17
	v_add_f32_e32 v24, v24, v15
	ds_read2st64_b32 v[14:15], v184 offset0:170 offset1:171
	ds_read2st64_b32 v[16:17], v184 offset0:162 offset1:163
	s_waitcnt lgkmcnt(3)
	v_add_f32_e32 v0, v0, v10
	s_waitcnt lgkmcnt(2)
	v_add_f32_e32 v18, v18, v12
	v_add_f32_e32 v19, v19, v11
	v_add_f32_e32 v20, v20, v13
	ds_read2st64_b32 v[10:11], v184 offset0:192 offset1:193
	ds_read2st64_b32 v[12:13], v184 offset0:200 offset1:201
	s_waitcnt lgkmcnt(2)
	v_add_f32_e32 v21, v21, v16
	v_add_f32_e32 v22, v22, v14
	v_add_f32_e32 v23, v23, v17
	v_add_f32_e32 v24, v24, v15
	ds_read2st64_b32 v[14:15], v184 offset0:202 offset1:203
	ds_read2st64_b32 v[16:17], v184 offset0:194 offset1:195
	s_waitcnt lgkmcnt(3)
	v_add_f32_e32 v0, v0, v10
	s_waitcnt lgkmcnt(2)
	v_add_f32_e32 v18, v18, v12
	v_add_f32_e32 v19, v19, v11
	v_add_f32_e32 v20, v20, v13
	ds_read2st64_b32 v[10:11], v184 offset0:224 offset1:225
	ds_read2st64_b32 v[12:13], v184 offset0:232 offset1:233
	s_waitcnt lgkmcnt(2)
	v_add_f32_e32 v21, v21, v16
	v_add_f32_e32 v22, v22, v14
	v_add_f32_e32 v23, v23, v17
	v_add_f32_e32 v24, v24, v15
	ds_read2st64_b32 v[14:15], v184 offset0:234 offset1:235
	ds_read2st64_b32 v[16:17], v184 offset0:226 offset1:227
	s_waitcnt lgkmcnt(3)
	v_add_f32_e32 v11, v19, v11
	s_waitcnt lgkmcnt(2)
	v_add_f32_e32 v19, v20, v13
	v_add_f32_e32 v25, v0, v10
	v_add_f32_e32 v18, v18, v12
	v_mul_f32_e32 v0, v11, v11
	v_mul_f32_e32 v10, v19, v19
	s_waitcnt lgkmcnt(0)
	v_add_f32_e32 v16, v21, v16
	v_add_f32_e32 v20, v22, v14
	v_fmac_f32_e32 v0, v25, v25
	v_fmac_f32_e32 v10, v18, v18
	v_add_f32_e32 v17, v23, v17
	v_add_f32_e32 v21, v24, v15
	v_fmac_f32_e32 v0, v16, v16
	v_fmac_f32_e32 v10, v20, v20
	v_fmac_f32_e32 v0, v17, v17
	v_fmac_f32_e32 v10, v21, v21
	v_add_f32_e32 v13, v0, v10
	v_and_b32_e32 v10, 64, v9
	v_xor_b32_e32 v0, 1, v9
	v_add_u32_e32 v22, 64, v10
	v_cmp_lt_i32_e64 s[4:5], v0, v22
	v_or_b32_e32 v10, s9, v182
	v_or_b32_e32 v12, s8, v7
	v_cndmask_b32_e64 v0, v9, v0, s[4:5]
	v_lshlrev_b32_e32 v0, 2, v0
	ds_bpermute_b32 v23, v0, v13
	v_lshlrev_b32_e32 v0, 11, v10
	v_lshl_add_u64 v[14:15], s[58:59], 0, v[0:1]
	s_waitcnt lgkmcnt(0)
	v_add_f32_e32 v0, v13, v23
	v_xor_b32_e32 v13, 2, v9
	v_cmp_lt_i32_e64 s[4:5], v13, v22
	s_nop 1
	v_cndmask_b32_e64 v13, v9, v13, s[4:5]
	v_lshlrev_b32_e32 v13, 2, v13
	ds_bpermute_b32 v23, v13, v0
	v_ashrrev_i32_e32 v13, 31, v12
	v_lshl_add_u64 v[12:13], v[12:13], 1, v[14:15]
	v_cvt_pk_bf16_f32 v14, v25, v11
	v_xor_b32_e32 v11, 4, v9
	v_cmp_lt_i32_e64 s[4:5], v11, v22
	s_waitcnt lgkmcnt(0)
	v_add_f32_e32 v0, v0, v23
	v_cvt_pk_bf16_f32 v15, v16, v17
	global_store_dwordx2 v[12:13], v[14:15], off
	v_cndmask_b32_e64 v11, v9, v11, s[4:5]
	v_lshlrev_b32_e32 v11, 2, v11
	ds_bpermute_b32 v11, v11, v0
	v_cvt_pk_bf16_f32 v14, v18, v19
	v_cvt_pk_bf16_f32 v15, v20, v21
	global_store_dwordx2 v[12:13], v[14:15], off offset:256
	s_and_b64 exec, exec, s[0:1]
	s_cbranch_execz .LBB0_770
	s_lshl_b32 s4, s19, 2
	s_or_b32 s4, s4, s20
	s_mul_hi_i32 s5, s4, 0x10800
	s_mul_i32 s4, s4, 0x10800
	s_add_u32 s4, s44, s4
	s_waitcnt lgkmcnt(0)
	v_add_f32_e32 v0, v0, v11
	s_addc_u32 s5, s45, s5
	v_lshlrev_b32_e32 v10, 2, v10
	global_store_dword v10, v0, s[4:5]
	s_branch .LBB0_770

.LBB0_777:
	s_lshl_b32 s0, s3, 3
	s_or_b32 s0, s0, s94
	s_mul_i32 s0, s0, s93
	s_add_i32 s0, s0, s95
	s_cmpk_gt_i32 s0, 0xff
	s_cbranch_scc1 .LBB0_776
	v_mov_b32_e32 v14, v136
	s_waitcnt lgkmcnt(0)
	s_barrier
	s_ashr_i32 s1, s0, 31
	v_ashrrev_i32_e32 v1, 31, v14
	v_lshrrev_b32_e32 v1, 26, v1
	v_add_u32_e32 v1, v14, v1
	v_ashrrev_i32_e32 v8, 6, v1
	v_bfe_i32 v1, v14, 27, 1
	v_lshlrev_b32_e32 v0, 4, v14
	v_lshrrev_b32_e32 v1, 22, v1
	v_add_u32_e32 v1, v0, v1
	v_and_b32_e32 v1, 0xfffffc00, v1
	v_sub_u32_e32 v1, v0, v1
	v_lshrrev_b32_e32 v2, 4, v1
	v_bitop3_b32 v1, v2, v1, 32 bitop3:0x6c
	v_ashrrev_i32_e32 v3, 31, v1
	v_lshrrev_b32_e32 v3, 26, v3
	v_add_u32_e32 v3, v1, v3
	v_ashrrev_i32_e32 v9, 6, v3
	v_and_b32_e32 v3, 0xc0, v3
	v_sub_u32_e32 v1, v1, v3
	s_lshr_b32 s1, s1, 27
	v_lshlrev_b32_e32 v2, 3, v8
	v_lshlrev_b32_e32 v4, 5, v8
	v_ashrrev_i16_sdwa v1, v133, sext(v1) dst_sel:DWORD dst_unused:UNUSED_PAD src0_sel:DWORD src1_sel:BYTE_0
	s_add_i32 s1, s0, s1
	v_and_b32_e32 v2, 0x1ffff0, v2
	v_and_b32_e32 v4, 32, v4
	v_bfe_i32 v11, v1, 0, 16
	s_ashr_i32 s34, s1, 5
	s_andn2_b32 s1, s1, 31
	v_add_u32_e32 v1, v4, v11
	v_add_lshl_u32 v2, v9, v2, 11
	v_add_u32_e32 v0, 0x2000, v0
	s_sub_i32 s1, s0, s1
	v_lshl_add_u32 v128, v1, 1, v2
	v_ashrrev_i32_e32 v1, 31, v0
	s_ashr_i32 s0, s1, 31
	v_lshrrev_b32_e32 v1, 22, v1
	s_lshr_b32 s0, s0, 29
	v_add_u32_e32 v1, v0, v1
	s_lshl_b32 s18, s34, 3
	s_add_i32 s19, s1, s0
	v_ashrrev_i32_e32 v10, 10, v1
	s_add_i32 s1, s1, s18
	s_and_b32 s35, s19, -8
	v_mul_i32_i24_e32 v1, 0x400, v10
	s_sub_i32 s18, s1, s35
	v_sub_u32_e32 v0, v0, v1
	s_ashr_i32 s0, s19, 3
	s_ashr_i32 s19, s18, 31
	v_lshrrev_b32_e32 v1, 4, v0
	s_lshl_b64 s[20:21], s[18:19], 19
	v_bitop3_b32 v0, v1, v0, 32 bitop3:0x6c
	s_add_u32 s20, s56, s20
	v_ashrrev_i32_e32 v2, 31, v0
	s_addc_u32 s21, s57, s21
	s_ashr_i32 s1, s0, 31
	v_readlane_b32 s72, v253, 51
	v_lshrrev_b32_e32 v2, 26, v2
	s_lshl_b64 s[22:23], s[0:1], 19
	v_readlane_b32 s84, v253, 63
	v_add_u32_e32 v2, v0, v2
	v_readlane_b32 s85, v254, 0
	s_add_u32 s24, s84, s22
	v_readfirstlane_b32 s1, v14
	v_ashrrev_i32_e32 v12, 6, v2
	v_and_b32_e32 v2, 0xc0, v2
	s_addc_u32 s25, s85, s23
	v_sub_u32_e32 v0, v0, v2
	s_ashr_i32 s33, s1, 6
	v_lshlrev_b32_e32 v1, 3, v10
	v_lshlrev_b32_e32 v3, 5, v10
	v_ashrrev_i16_sdwa v0, v133, sext(v0) dst_sel:DWORD dst_unused:UNUSED_PAD src0_sel:DWORD src1_sel:BYTE_0
	s_lshl_b32 s19, s33, 10
	v_and_b32_e32 v1, 0x1ffff0, v1
	v_and_b32_e32 v3, 32, v3
	v_bfe_i32 v13, v0, 0, 16
	s_add_i32 s27, s19, 0
	v_add_u32_e32 v0, v3, v13
	v_add_lshl_u32 v1, v12, v1, 11
	s_add_i32 m0, s27, 0x10000
	v_lshl_add_u32 v130, v0, 1, v1
	s_add_i32 m0, s27, 0x12000
	s_ashr_i32 s31, s1, 8
	s_mov_b32 m0, s27
	s_add_i32 s28, s27, 0x2000
	s_mov_b32 m0, s28
	s_add_u32 s36, s24, 0x40000
	s_addc_u32 s37, s25, 0
	s_add_i32 m0, s27, 0x14000
	v_mov_b32_e32 v131, v129
	s_add_i32 m0, s27, 0x16000
	v_lshl_add_u64 v[6:7], s[24:25], 0, v[128:129]
	s_add_u32 s36, s20, 0x40000
	s_addc_u32 s37, s21, 0
	s_add_i32 s29, s27, 0x4000
	s_mov_b32 m0, s29
	s_add_i32 s30, s27, 0x6000
	s_mov_b32 m0, s30
	v_lshl_add_u64 v[4:5], s[24:25], 0, v[130:131]
	v_lshl_add_u64 v[2:3], s[20:21], 0, v[128:129]
	s_cmp_lg_u32 s31, 1
	v_lshl_add_u64 v[0:1], s[20:21], 0, v[130:131]
	v_readlane_b32 s73, v253, 52
	v_readlane_b32 s74, v253, 53
	v_readlane_b32 s75, v253, 54
	v_readlane_b32 s76, v253, 55
	v_readlane_b32 s77, v253, 56
	v_readlane_b32 s78, v253, 57
	v_readlane_b32 s79, v253, 58
	v_readlane_b32 s80, v253, 59
	v_readlane_b32 s81, v253, 60
	v_readlane_b32 s82, v253, 61
	v_readlane_b32 s83, v253, 62
	v_readlane_b32 s86, v254, 1
	v_readlane_b32 s87, v254, 2
	s_cbranch_scc1 .LBB0_780
	s_barrier
.LBB0_780:
	v_and_b32_e32 v15, 15, v14
	v_and_b32_e32 v16, 48, v14
	v_lshlrev_b32_e32 v14, 2, v14
	v_lshlrev_b32_e32 v15, 6, v15
	v_and_b32_e32 v14, 32, v14
	s_lshl_b32 s33, s33, 12
	v_or_b32_e32 v17, v15, v16
	v_bitop3_b32 v15, v15, v14, v16 bitop3:0x36
	s_lshl_b32 s31, s31, 13
	s_and_b32 s33, s33, 0x3000
	s_add_i32 m0, s27, 0x18000
	v_lshl_add_u64 v[6:7], v[6:7], 0, s[4:5]
	v_or_b32_e32 v145, s33, v15
	v_bitop3_b32 v14, v17, s31, v14 bitop3:0xde
	s_waitcnt vmcnt(0)
	s_barrier
	global_load_lds_dwordx4 v[6:7], off
	v_lshl_add_u64 v[4:5], v[4:5], 0, s[4:5]
	s_add_i32 m0, s27, 0x1a000
	s_add_i32 s31, s27, 0x8000
	s_add_i32 s33, s27, 0xa000
	global_load_lds_dwordx4 v[4:5], off
	v_lshl_add_u64 v[2:3], v[2:3], 0, s[4:5]
	s_mov_b32 m0, s31
	s_add_u32 s24, s24, 0x40080
	global_load_lds_dwordx4 v[2:3], off
	v_lshl_add_u64 v[0:1], v[0:1], 0, s[4:5]
	s_mov_b32 m0, s33
	s_addc_u32 s25, s25, 0
	global_load_lds_dwordx4 v[0:1], off
	s_add_i32 m0, s27, 0x1c000
	v_lshl_add_u64 v[0:1], s[24:25], 0, v[128:129]
	global_load_lds_dwordx4 v[0:1], off
	v_lshl_add_u64 v[0:1], s[24:25], 0, v[130:131]
	s_add_i32 m0, s27, 0x1e000
	s_sub_i32 s24, s26, s35
	global_load_lds_dwordx4 v[0:1], off
	s_mul_i32 s34, s34, 24
	s_sub_i32 s24, s24, s34
	s_ashr_i32 s25, s24, 31
	s_lshl_b64 s[24:25], s[24:25], 19
	v_lshlrev_b32_e32 v0, 14, v8
	v_and_b32_e32 v0, 0xffff8000, v0
	s_add_u32 s24, s56, s24
	v_lshlrev_b32_e32 v2, 14, v10
	v_readlane_b32 s72, v253, 51
	v_lshl_add_u32 v0, v9, 11, v0
	v_and_b32_e32 v1, 1, v8
	s_addc_u32 s25, s57, s25
	v_and_b32_e32 v2, 0xffff8000, v2
	v_readlane_b32 s84, v253, 63
	v_lshl_or_b32 v0, v1, 6, v0
	v_lshl_add_u32 v2, v12, 11, v2
	v_and_b32_e32 v3, 1, v10
	v_readlane_b32 s85, v254, 0
	s_add_u32 s22, s84, s22
	s_waitcnt vmcnt(6)
	v_lshl_add_u32 v0, v11, 1, v0
	v_mov_b32_e32 v1, v129
	v_lshl_or_b32 v2, v3, 6, v2
	s_addc_u32 s23, s85, s23
	v_lshl_add_u64 v[134:135], s[24:25], 0, v[0:1]
	v_lshl_add_u32 v2, v13, 1, v2
	v_mov_b32_e32 v3, v129
	v_lshl_add_u64 v[140:141], s[22:23], 0, v[0:1]
	v_mov_b32_e32 v0, 0
	v_lshl_add_u64 v[138:139], s[24:25], 0, v[2:3]
	v_lshl_add_u64 v[142:143], s[22:23], 0, v[2:3]
	s_mov_b32 s25, -2
	s_mov_b64 s[22:23], 0
	v_add_u32_e32 v146, s42, v145
	v_add_u32_e32 v144, 0, v14
	s_add_i32 s34, s27, 0xc000
	s_add_i32 s24, s27, 0xe000
	v_add_u32_e32 v147, s43, v145
	v_mov_b32_e32 v1, v0
	v_mov_b32_e32 v2, v0
	v_mov_b32_e32 v3, v0
	v_mov_b32_e32 v4, v0
	v_mov_b32_e32 v5, v0
	v_mov_b32_e32 v6, v0
	v_mov_b32_e32 v7, v0
	v_mov_b32_e32 v8, v0
	v_mov_b32_e32 v9, v0
	v_mov_b32_e32 v10, v0
	v_mov_b32_e32 v11, v0
	v_mov_b32_e32 v12, v0
	v_mov_b32_e32 v13, v0
	v_mov_b32_e32 v14, v0
	v_mov_b32_e32 v15, v0
	v_mov_b32_e32 v16, v0
	v_mov_b32_e32 v17, v0
	v_mov_b32_e32 v18, v0
	v_mov_b32_e32 v19, v0
	v_mov_b32_e32 v20, v0
	v_mov_b32_e32 v21, v0
	v_mov_b32_e32 v22, v0
	v_mov_b32_e32 v23, v0
	v_mov_b32_e32 v24, v0
	v_mov_b32_e32 v25, v0
	v_mov_b32_e32 v26, v0
	v_mov_b32_e32 v27, v0
	v_mov_b32_e32 v28, v0
	v_mov_b32_e32 v29, v0
	v_mov_b32_e32 v30, v0
	v_mov_b32_e32 v31, v0
	v_mov_b32_e32 v32, v0
	v_mov_b32_e32 v33, v0
	v_mov_b32_e32 v34, v0
	v_mov_b32_e32 v35, v0
	v_mov_b32_e32 v36, v0
	v_mov_b32_e32 v37, v0
	v_mov_b32_e32 v38, v0
	v_mov_b32_e32 v39, v0
	v_mov_b32_e32 v40, v0
	v_mov_b32_e32 v41, v0
	v_mov_b32_e32 v42, v0
	v_mov_b32_e32 v43, v0
	v_mov_b32_e32 v44, v0
	v_mov_b32_e32 v45, v0
	v_mov_b32_e32 v46, v0
	v_mov_b32_e32 v47, v0
	v_mov_b32_e32 v48, v0
	v_mov_b32_e32 v49, v0
	v_mov_b32_e32 v50, v0
	v_mov_b32_e32 v51, v0
	v_mov_b32_e32 v52, v0
	v_mov_b32_e32 v53, v0
	v_mov_b32_e32 v54, v0
	v_mov_b32_e32 v55, v0
	v_mov_b32_e32 v56, v0
	v_mov_b32_e32 v57, v0
	v_mov_b32_e32 v58, v0
	v_mov_b32_e32 v59, v0
	v_mov_b32_e32 v60, v0
	v_mov_b32_e32 v61, v0
	v_mov_b32_e32 v62, v0
	v_mov_b32_e32 v63, v0
	v_mov_b32_e32 v64, v0
	v_mov_b32_e32 v65, v0
	v_mov_b32_e32 v66, v0
	v_mov_b32_e32 v67, v0
	v_mov_b32_e32 v68, v0
	v_mov_b32_e32 v69, v0
	v_mov_b32_e32 v70, v0
	v_mov_b32_e32 v71, v0
	v_mov_b32_e32 v72, v0
	v_mov_b32_e32 v73, v0
	v_mov_b32_e32 v74, v0
	v_mov_b32_e32 v75, v0
	v_mov_b32_e32 v76, v0
	v_mov_b32_e32 v77, v0
	v_mov_b32_e32 v78, v0
	v_mov_b32_e32 v79, v0
	v_mov_b32_e32 v80, v0
	v_mov_b32_e32 v81, v0
	v_mov_b32_e32 v82, v0
	v_mov_b32_e32 v83, v0
	v_mov_b32_e32 v84, v0
	v_mov_b32_e32 v85, v0
	v_mov_b32_e32 v86, v0
	v_mov_b32_e32 v87, v0
	v_mov_b32_e32 v88, v0
	v_mov_b32_e32 v89, v0
	v_mov_b32_e32 v90, v0
	v_mov_b32_e32 v91, v0
	v_mov_b32_e32 v92, v0
	v_mov_b32_e32 v93, v0
	v_mov_b32_e32 v94, v0
	v_mov_b32_e32 v95, v0
	v_mov_b32_e32 v96, v0
	v_mov_b32_e32 v97, v0
	v_mov_b32_e32 v98, v0
	v_mov_b32_e32 v99, v0
	v_mov_b32_e32 v100, v0
	v_mov_b32_e32 v101, v0
	v_mov_b32_e32 v102, v0
	v_mov_b32_e32 v103, v0
	v_mov_b32_e32 v104, v0
	v_mov_b32_e32 v105, v0
	v_mov_b32_e32 v106, v0
	v_mov_b32_e32 v107, v0
	v_mov_b32_e32 v108, v0
	v_mov_b32_e32 v109, v0
	v_mov_b32_e32 v110, v0
	v_mov_b32_e32 v111, v0
	v_mov_b32_e32 v112, v0
	v_mov_b32_e32 v113, v0
	v_mov_b32_e32 v114, v0
	v_mov_b32_e32 v115, v0
	v_mov_b32_e32 v116, v0
	v_mov_b32_e32 v117, v0
	v_mov_b32_e32 v118, v0
	v_mov_b32_e32 v119, v0
	v_mov_b32_e32 v120, v0
	v_mov_b32_e32 v121, v0
	v_mov_b32_e32 v122, v0
	v_mov_b32_e32 v123, v0
	v_mov_b32_e32 v124, v0
	v_mov_b32_e32 v125, v0
	v_mov_b32_e32 v126, v0
	v_mov_b32_e32 v127, v0
	s_barrier
	v_readlane_b32 s73, v253, 52
	v_readlane_b32 s74, v253, 53
	v_readlane_b32 s75, v253, 54
	v_readlane_b32 s76, v253, 55
	v_readlane_b32 s77, v253, 56
	v_readlane_b32 s78, v253, 57
	v_readlane_b32 s79, v253, 58
	v_readlane_b32 s80, v253, 59
	v_readlane_b32 s81, v253, 60
	v_readlane_b32 s82, v253, 61
	v_readlane_b32 s83, v253, 62
	v_readlane_b32 s86, v254, 1
	v_readlane_b32 s87, v254, 2

.LBB0_1159:
	s_or_b64 exec, exec, s[0:1]
	s_and_b64 vcc, exec, s[4:5]
	s_waitcnt lgkmcnt(0)
	s_barrier
	v_lshlrev_b32_e32 v150, 4, v136
	v_and_b32_e32 v151, 0x3ff, v150
	v_lshrrev_b32_e32 v152, 4, v151
	v_and_b32_e32 v152, 32, v152
	v_xor_b32_e32 v151, v151, v152
	v_lshrrev_b32_e32 v152, 10, v150
	v_lshrrev_b32_e32 v153, 1, v152
	v_lshlrev_b32_e32 v153, 4, v153
	v_lshrrev_b32_e32 v150, 6, v151
	v_add_u32_e32 v153, v153, v150
	v_mul_u32_u24_e32 v153, 0x800, v153
	v_and_b32_e32 v152, 1, v152
	v_lshl_add_u32 v153, v152, 6, v153
	v_and_b32_e32 v151, 63, v151
	v_add_u32_e32 v150, v153, v151
	v_add_u32_e32 v151, 0x20000, v150
	s_and_b32 s72, s2, 7
	s_lshl_b32 s72, s72, 3
	s_bfe_u32 s73, s2, 0x30003
	s_or_b32 s72, s72, s73
	s_mul_i32 s72, s72, 0x80000
	s_add_u32 s74, s70, s72
	s_addc_u32 s75, s71, 0
	v_readlane_b32 s76, v254, 4
	v_readlane_b32 s77, v254, 5
	s_lshr_b32 s72, s2, 6
	s_mul_i32 s72, s72, 0x80000
	s_nop 0
	s_add_u32 s76, s76, s72
	s_addc_u32 s77, s77, 0
	s_add_u32 s78, s76, 0x40000
	s_addc_u32 s79, s77, 0
	s_add_u32 s80, s74, 0x40000
	s_addc_u32 s81, s75, 0
	v_readfirstlane_b32 s82, v136
	s_nop 0
	s_lshr_b32 s82, s82, 6
	s_lshl_b32 s82, s82, 10
	s_add_i32 m0, s82, 0x10000
	s_nop 0
	global_load_lds_dwordx4 v150, s[76:77]
	s_add_i32 m0, s82, 0x12000
	s_nop 0
	global_load_lds_dwordx4 v151, s[76:77]
	s_add_i32 m0, s82, 0x0
	s_nop 0
	global_load_lds_dwordx4 v150, s[74:75]
	s_add_i32 m0, s82, 0x2000
	s_nop 0
	global_load_lds_dwordx4 v151, s[74:75]
	s_add_i32 m0, s82, 0x14000
	s_nop 0
	global_load_lds_dwordx4 v150, s[78:79]
	s_add_i32 m0, s82, 0x16000
	s_nop 0
	global_load_lds_dwordx4 v151, s[78:79]
	s_add_i32 m0, s82, 0x4000
	s_nop 0
	global_load_lds_dwordx4 v150, s[80:81]
	s_add_i32 m0, s82, 0x6000
	s_nop 0
	global_load_lds_dwordx4 v151, s[80:81]
	s_cbranch_vccnz .LBB0_1165
	v_readlane_b32 s12, v254, 4
	v_and_b32_e32 v0, 0x7800, v190
	v_mov_b32_e32 v1, 0
	v_readlane_b32 s13, v254, 5
	v_mov_b32_e32 v133, v1
	v_and_b32_e32 v7, 4, v188
	v_lshl_add_u64 v[2:3], s[12:13], 0, v[0:1]
	v_lshl_add_u64 v[4:5], v[2:3], 0, v[132:133]
	v_lshl_add_u64 v[2:3], s[70:71], 0, v[0:1]
	v_and_or_b32 v6, v182, 16, v7
	v_lshl_add_u64 v[2:3], v[2:3], 0, v[132:133]
	v_lshlrev_b32_e32 v0, 8, v187
	v_and_b32_e32 v9, 60, v252
	v_lshlrev_b32_e32 v6, 8, v6
	v_readlane_b32 s16, v254, 8
	v_readlane_b32 s17, v254, 9
	v_readlane_b32 s18, v254, 10
	v_readlane_b32 s19, v254, 11
	v_readlane_b32 s20, v254, 12
	v_lshl_add_u64 v[2:3], v[2:3], 0, v[0:1]
	v_lshl_add_u64 v[4:5], v[4:5], 0, v[0:1]
	v_lshlrev_b32_e32 v0, 13, v187
	v_lshl_add_u32 v8, v189, 2, 0
	s_movk_i32 s0, 0x100
	v_add3_u32 v6, v186, v9, v6
	v_and_b32_e32 v9, 7, v136
	s_mov_b32 s11, 0
	v_cmp_gt_u32_e32 vcc, s0, v136
	v_lshl_or_b32 v7, v183, 3, v7
	v_cmp_eq_u32_e64 s[0:1], 0, v9
	s_lshl_b32 s3, s2, 5
	s_lshl_b32 s16, s38, 5
	s_mov_b32 s17, 0x8000
	s_mov_b32 s18, 0x40000
	s_mov_b32 s19, 0x48000
	v_add_u32_e32 v8, v8, v0
	v_lshrrev_b32_e32 v185, 2, v187
	v_lshl_add_u32 v8, v185, 15, v8
	v_add_u32_e32 v8, 0x8000, v8
	v_add_u32_e32 v184, 0x10000, v6
	s_mov_b32 s20, s2
	v_readlane_b32 s14, v254, 6
	v_readlane_b32 s15, v254, 7
	v_readlane_b32 s21, v254, 13
	v_readlane_b32 s22, v254, 14
	v_readlane_b32 s23, v254, 15
	v_readlane_b32 s24, v254, 16
	v_readlane_b32 s25, v254, 17
	v_readlane_b32 s26, v254, 18
	v_readlane_b32 s27, v254, 19
	s_branch .LBB0_1162

.LBB0_1162:
	s_ashr_i32 s21, s20, 6
	s_bfe_u32 s22, s20, 0x20004
	s_lshl_b32 s6, s21, 8
	s_lshl_b32 s7, s22, 5
	s_or_b32 s12, s7, s6
	s_and_b32 s10, s3, 0x1e0
	s_ashr_i32 s13, s12, 31
	s_lshl_b64 s[6:7], s[12:13], 11
	s_or_b32 s13, s10, 0x4000
	s_lshl_b32 s10, s13, 11
	v_lshl_add_u64 v[72:73], v[2:3], 0, s[10:11]
	v_lshl_add_u64 v[70:71], v[4:5], 0, s[6:7]
	v_add_co_u32_e64 v74, s[6:7], s17, v72
	s_waitcnt lgkmcnt(0)
	global_load_dwordx4 v[10:13], v[70:71], off
	v_addc_co_u32_e64 v75, s[6:7], 0, v73, s[6:7]
	v_add_co_u32_e64 v76, s[6:7], s17, v70
	global_load_dwordx4 v[14:17], v[72:73], off
	s_nop 0
	v_addc_co_u32_e64 v77, s[6:7], 0, v71, s[6:7]
	v_add_co_u32_e64 v78, s[6:7], s18, v70
	global_load_dwordx4 v[18:21], v[72:73], off offset:64
	global_load_dwordx4 v[22:25], v[74:75], off
	v_addc_co_u32_e64 v79, s[6:7], 0, v71, s[6:7]
	v_add_co_u32_e64 v80, s[6:7], s19, v70
	global_load_dwordx4 v[26:29], v[70:71], off offset:64
	s_nop 0
	v_addc_co_u32_e64 v81, s[6:7], 0, v71, s[6:7]
	global_load_dwordx4 v[34:37], v[76:77], off
	global_load_dwordx4 v[38:41], v[74:75], off offset:64
	global_load_dwordx4 v[42:45], v[76:77], off offset:64
	global_load_dwordx4 v[50:53], v[78:79], off
	global_load_dwordx4 v[54:57], v[78:79], off offset:64
	global_load_dwordx4 v[62:65], v[80:81], off
	global_load_dwordx4 v[66:69], v[80:81], off offset:64
	s_waitcnt vmcnt(10)
	v_mfma_f32_16x16x32_bf16 v[30:33], v[10:13], v[14:17], 0
	s_waitcnt vmcnt(8)
	v_mfma_f32_16x16x32_bf16 v[10:13], v[10:13], v[22:25], 0
	s_waitcnt vmcnt(6)
	v_mfma_f32_16x16x32_bf16 v[46:49], v[34:37], v[14:17], 0
	v_mfma_f32_16x16x32_bf16 v[34:37], v[34:37], v[22:25], 0
	s_waitcnt vmcnt(3)
	v_mfma_f32_16x16x32_bf16 v[58:61], v[50:53], v[14:17], 0
	s_waitcnt vmcnt(1)
	v_mfma_f32_16x16x32_bf16 v[14:17], v[62:65], v[14:17], 0
	v_mfma_f32_16x16x32_bf16 v[30:33], v[26:29], v[18:21], v[30:33]
	v_mfma_f32_16x16x32_bf16 v[10:13], v[26:29], v[38:41], v[10:13]
	v_mfma_f32_16x16x32_bf16 v[26:29], v[42:45], v[18:21], v[46:49]
	v_mfma_f32_16x16x32_bf16 v[34:37], v[42:45], v[38:41], v[34:37]
	v_mfma_f32_16x16x32_bf16 v[42:45], v[54:57], v[18:21], v[58:61]
	s_waitcnt vmcnt(0)
	v_mfma_f32_16x16x32_bf16 v[14:17], v[66:69], v[18:21], v[14:17]
	global_load_dwordx4 v[18:21], v[70:71], off offset:128
	v_mfma_f32_16x16x32_bf16 v[50:53], v[50:53], v[22:25], 0
	v_mfma_f32_16x16x32_bf16 v[22:25], v[62:65], v[22:25], 0
	v_mfma_f32_16x16x32_bf16 v[46:49], v[54:57], v[38:41], v[50:53]
	v_mfma_f32_16x16x32_bf16 v[22:25], v[66:69], v[38:41], v[22:25]
	global_load_dwordx4 v[38:41], v[72:73], off offset:128
	s_nop 3
	global_load_dwordx4 v[50:53], v[72:73], off offset:192
	global_load_dwordx4 v[54:57], v[70:71], off offset:192
	global_load_dwordx4 v[58:61], v[74:75], off offset:128
	global_load_dwordx4 v[62:65], v[74:75], off offset:192
	s_waitcnt vmcnt(4)
	v_mfma_f32_16x16x32_bf16 v[30:33], v[18:21], v[38:41], v[30:33]
	s_waitcnt vmcnt(1)
	v_mfma_f32_16x16x32_bf16 v[10:13], v[18:21], v[58:61], v[10:13]
	global_load_dwordx4 v[18:21], v[76:77], off offset:128
	global_load_dwordx4 v[66:69], v[76:77], off offset:192
	v_mfma_f32_16x16x32_bf16 v[30:33], v[54:57], v[50:53], v[30:33]
	s_waitcnt vmcnt(2)
	v_mfma_f32_16x16x32_bf16 v[10:13], v[54:57], v[62:65], v[10:13]
	s_waitcnt vmcnt(1)
	v_mfma_f32_16x16x32_bf16 v[26:29], v[18:21], v[38:41], v[26:29]
	v_mfma_f32_16x16x32_bf16 v[18:21], v[18:21], v[58:61], v[34:37]
	s_nop 2
	global_load_dwordx4 v[34:37], v[78:79], off offset:128
	global_load_dwordx4 v[70:73], v[78:79], off offset:192
	global_load_dwordx4 v[74:77], v[80:81], off offset:128
	s_waitcnt vmcnt(3)
	v_mfma_f32_16x16x32_bf16 v[26:29], v[66:69], v[50:53], v[26:29]
	s_waitcnt vmcnt(2)
	v_mfma_f32_16x16x32_bf16 v[42:45], v[34:37], v[38:41], v[42:45]
	v_mfma_f32_16x16x32_bf16 v[34:37], v[34:37], v[58:61], v[46:49]
	s_nop 2
	global_load_dwordx4 v[46:49], v[80:81], off offset:192
	s_waitcnt vmcnt(1)
	v_mfma_f32_16x16x32_bf16 v[14:17], v[74:77], v[38:41], v[14:17]
	s_barrier
	ds_write2st64_b32 v8, v30, v31 offset1:1
	ds_write2st64_b32 v8, v32, v33 offset0:2 offset1:3
	v_mfma_f32_16x16x32_bf16 v[30:33], v[70:73], v[50:53], v[42:45]
	ds_write2st64_b32 v8, v26, v27 offset0:4 offset1:5
	ds_write2st64_b32 v8, v28, v29 offset0:6 offset1:7
	s_nop 5
	ds_write2st64_b32 v8, v30, v31 offset0:8 offset1:9
	v_mfma_f32_16x16x32_bf16 v[22:25], v[74:77], v[58:61], v[22:25]
	s_waitcnt vmcnt(0)
	v_mfma_f32_16x16x32_bf16 v[14:17], v[46:49], v[50:53], v[14:17]
	ds_write2st64_b32 v8, v32, v33 offset0:10 offset1:11
	s_nop 6
	ds_write2st64_b32 v8, v14, v15 offset0:12 offset1:13
	ds_write2st64_b32 v8, v16, v17 offset0:14 offset1:15
	v_mfma_f32_16x16x32_bf16 v[14:17], v[66:69], v[62:65], v[18:21]
	ds_write2st64_b32 v8, v10, v11 offset0:16 offset1:17
	ds_write2st64_b32 v8, v12, v13 offset0:18 offset1:19
	s_nop 5
	ds_write2st64_b32 v8, v14, v15 offset0:20 offset1:21
	v_mfma_f32_16x16x32_bf16 v[10:13], v[70:73], v[62:65], v[34:37]
	ds_write2st64_b32 v8, v16, v17 offset0:22 offset1:23
	s_nop 6
	ds_write2st64_b32 v8, v10, v11 offset0:24 offset1:25
	ds_write2st64_b32 v8, v12, v13 offset0:26 offset1:27
	v_mfma_f32_16x16x32_bf16 v[10:13], v[46:49], v[62:65], v[22:25]
	s_nop 7
	ds_write2st64_b32 v8, v10, v11 offset0:28 offset1:29
	ds_write2st64_b32 v8, v12, v13 offset0:30 offset1:31
	s_waitcnt lgkmcnt(0)
	s_barrier
	s_and_saveexec_b64 s[14:15], vcc
	s_cbranch_execz .LBB0_1161
	ds_read2st64_b32 v[10:11], v6 offset0:128 offset1:129
	ds_read2st64_b32 v[12:13], v6 offset0:136 offset1:137
	ds_read2st64_b32 v[14:15], v6 offset0:138 offset1:139
	ds_read2st64_b32 v[16:17], v6 offset0:130 offset1:131
	s_waitcnt lgkmcnt(3)
	v_add_f32_e32 v0, 0, v10
	s_waitcnt lgkmcnt(2)
	v_add_f32_e32 v9, 0, v12
	v_add_f32_e32 v18, 0, v11
	v_add_f32_e32 v19, 0, v13
	ds_read2st64_b32 v[10:11], v6 offset0:160 offset1:161
	ds_read2st64_b32 v[12:13], v6 offset0:168 offset1:169
	s_waitcnt lgkmcnt(2)
	v_add_f32_e32 v20, 0, v16
	v_add_f32_e32 v21, 0, v14
	v_add_f32_e32 v22, 0, v17
	v_add_f32_e32 v23, 0, v15
	ds_read2st64_b32 v[14:15], v6 offset0:170 offset1:171
	ds_read2st64_b32 v[16:17], v6 offset0:162 offset1:163
	s_waitcnt lgkmcnt(3)
	v_add_f32_e32 v0, v0, v10
	s_waitcnt lgkmcnt(2)
	v_add_f32_e32 v9, v9, v12
	v_add_f32_e32 v18, v18, v11
	v_add_f32_e32 v19, v19, v13
	ds_read2st64_b32 v[10:11], v6 offset0:192 offset1:193
	ds_read2st64_b32 v[12:13], v6 offset0:200 offset1:201
	s_waitcnt lgkmcnt(2)
	v_add_f32_e32 v20, v20, v16
	v_add_f32_e32 v21, v21, v14
	v_add_f32_e32 v22, v22, v17
	v_add_f32_e32 v23, v23, v15
	ds_read2st64_b32 v[14:15], v6 offset0:202 offset1:203
	ds_read2st64_b32 v[16:17], v6 offset0:194 offset1:195
	s_waitcnt lgkmcnt(3)
	v_add_f32_e32 v0, v0, v10
	s_waitcnt lgkmcnt(2)
	v_add_f32_e32 v9, v9, v12
	v_add_f32_e32 v18, v18, v11
	v_add_f32_e32 v19, v19, v13
	ds_read2st64_b32 v[10:11], v6 offset0:224 offset1:225
	ds_read2st64_b32 v[12:13], v6 offset0:232 offset1:233
	s_waitcnt lgkmcnt(2)
	v_add_f32_e32 v20, v20, v16
	v_add_f32_e32 v21, v21, v14
	v_add_f32_e32 v22, v22, v17
	v_add_f32_e32 v23, v23, v15
	ds_read2st64_b32 v[14:15], v6 offset0:234 offset1:235
	ds_read2st64_b32 v[16:17], v6 offset0:226 offset1:227
	s_waitcnt lgkmcnt(3)
	v_add_f32_e32 v0, v0, v10
	s_waitcnt lgkmcnt(2)
	v_add_f32_e32 v9, v9, v12
	v_add_f32_e32 v18, v18, v11
	v_add_f32_e32 v19, v19, v13
	ds_read2st64_b32 v[10:11], v184 offset0:128 offset1:129
	ds_read2st64_b32 v[12:13], v184 offset0:136 offset1:137
	s_waitcnt lgkmcnt(2)
	v_add_f32_e32 v20, v20, v16
	v_add_f32_e32 v21, v21, v14
	v_add_f32_e32 v22, v22, v17
	v_add_f32_e32 v23, v23, v15
	ds_read2st64_b32 v[14:15], v184 offset0:138 offset1:139
	ds_read2st64_b32 v[16:17], v184 offset0:130 offset1:131
	s_waitcnt lgkmcnt(3)
	v_add_f32_e32 v0, v0, v10
	s_waitcnt lgkmcnt(2)
	v_add_f32_e32 v9, v9, v12
	v_add_f32_e32 v18, v18, v11
	v_add_f32_e32 v19, v19, v13
	ds_read2st64_b32 v[10:11], v184 offset0:160 offset1:161
	ds_read2st64_b32 v[12:13], v184 offset0:168 offset1:169
	s_waitcnt lgkmcnt(2)
	v_add_f32_e32 v20, v20, v16
	v_add_f32_e32 v21, v21, v14
	v_add_f32_e32 v22, v22, v17
	v_add_f32_e32 v23, v23, v15
	ds_read2st64_b32 v[14:15], v184 offset0:170 offset1:171
	ds_read2st64_b32 v[16:17], v184 offset0:162 offset1:163
	s_waitcnt lgkmcnt(3)
	v_add_f32_e32 v0, v0, v10
	s_waitcnt lgkmcnt(2)
	v_add_f32_e32 v9, v9, v12
	v_add_f32_e32 v18, v18, v11
	v_add_f32_e32 v19, v19, v13
	ds_read2st64_b32 v[10:11], v184 offset0:192 offset1:193
	ds_read2st64_b32 v[12:13], v184 offset0:200 offset1:201
	s_waitcnt lgkmcnt(2)
	v_add_f32_e32 v20, v20, v16
	v_add_f32_e32 v21, v21, v14
	v_add_f32_e32 v22, v22, v17
	v_add_f32_e32 v23, v23, v15
	ds_read2st64_b32 v[14:15], v184 offset0:202 offset1:203
	ds_read2st64_b32 v[16:17], v184 offset0:194 offset1:195
	s_waitcnt lgkmcnt(3)
	v_add_f32_e32 v0, v0, v10
	s_waitcnt lgkmcnt(2)
	v_add_f32_e32 v9, v9, v12
	v_add_f32_e32 v18, v18, v11
	v_add_f32_e32 v19, v19, v13
	ds_read2st64_b32 v[10:11], v184 offset0:224 offset1:225
	ds_read2st64_b32 v[12:13], v184 offset0:232 offset1:233
	s_waitcnt lgkmcnt(2)
	v_add_f32_e32 v20, v20, v16
	v_add_f32_e32 v21, v21, v14
	v_add_f32_e32 v22, v22, v17
	v_add_f32_e32 v23, v23, v15
	ds_read2st64_b32 v[14:15], v184 offset0:234 offset1:235
	ds_read2st64_b32 v[16:17], v184 offset0:226 offset1:227
	s_waitcnt lgkmcnt(3)
	v_add_f32_e32 v18, v18, v11
	s_waitcnt lgkmcnt(2)
	v_add_f32_e32 v19, v19, v13
	v_add_f32_e32 v24, v0, v10
	v_add_f32_e32 v25, v9, v12
	v_mul_f32_e32 v0, v18, v18
	v_mul_f32_e32 v9, v19, v19
	s_waitcnt lgkmcnt(0)
	v_add_f32_e32 v16, v20, v16
	v_add_f32_e32 v20, v21, v14
	v_fmac_f32_e32 v0, v24, v24
	v_fmac_f32_e32 v9, v25, v25
	v_add_f32_e32 v17, v22, v17
	v_add_f32_e32 v21, v23, v15
	v_fmac_f32_e32 v0, v16, v16
	v_fmac_f32_e32 v9, v20, v20
	v_fmac_f32_e32 v0, v17, v17
	v_fmac_f32_e32 v9, v21, v21
	v_add_f32_e32 v11, v0, v9
	v_and_b32_e32 v9, 64, v137
	v_xor_b32_e32 v0, 1, v137
	v_add_u32_e32 v22, 64, v9
	v_cmp_lt_i32_e64 s[6:7], v0, v22
	v_or_b32_e32 v9, s13, v182
	v_or_b32_e32 v10, s12, v7
	v_cndmask_b32_e64 v0, v137, v0, s[6:7]
	v_lshlrev_b32_e32 v0, 2, v0
	ds_bpermute_b32 v14, v0, v11
	v_lshlrev_b32_e32 v0, 11, v9
	v_lshl_add_u64 v[12:13], s[58:59], 0, v[0:1]
	v_cvt_pk_bf16_f32 v15, v16, v17
	s_waitcnt lgkmcnt(0)
	v_add_f32_e32 v0, v11, v14
	v_xor_b32_e32 v11, 2, v137
	v_cmp_lt_i32_e64 s[6:7], v11, v22
	v_cvt_pk_bf16_f32 v14, v24, v18
	s_nop 1
	v_cndmask_b32_e64 v11, v137, v11, s[6:7]
	v_lshlrev_b32_e32 v11, 2, v11
	ds_bpermute_b32 v23, v11, v0
	v_ashrrev_i32_e32 v11, 31, v10
	v_lshl_add_u64 v[12:13], v[10:11], 1, v[12:13]
	v_xor_b32_e32 v10, 4, v137
	v_cmp_lt_i32_e64 s[6:7], v10, v22
	s_waitcnt lgkmcnt(0)
	v_add_f32_e32 v0, v0, v23
	global_store_dwordx2 v[12:13], v[14:15], off
	v_cndmask_b32_e64 v10, v137, v10, s[6:7]
	v_lshlrev_b32_e32 v10, 2, v10
	ds_bpermute_b32 v10, v10, v0
	v_cvt_pk_bf16_f32 v14, v25, v19
	v_cvt_pk_bf16_f32 v15, v20, v21
	global_store_dwordx2 v[12:13], v[14:15], off offset:256
	s_and_b64 exec, exec, s[0:1]
	s_cbranch_execz .LBB0_1161
	s_lshl_b32 s6, s21, 2
	s_or_b32 s6, s6, s22
	s_mul_hi_i32 s7, s6, 0x10800
	s_mul_i32 s6, s6, 0x10800
	s_add_u32 s6, s44, s6
	s_waitcnt lgkmcnt(0)
	v_add_f32_e32 v0, v0, v10
	s_addc_u32 s7, s45, s7
	v_lshlrev_b32_e32 v9, 2, v9
	global_store_dword v9, v0, s[6:7]
	s_branch .LBB0_1161

.LBB0_1168:
	s_lshl_b32 s0, s3, 3
	s_or_b32 s0, s0, s94
	s_mul_i32 s0, s0, s93
	s_add_i32 s0, s0, s95
	s_cmpk_gt_i32 s0, 0xff
	s_cbranch_scc1 .LBB0_1167
	v_mov_b32_e32 v14, v136
	s_waitcnt lgkmcnt(0)
	s_barrier
	s_ashr_i32 s1, s0, 31
	v_ashrrev_i32_e32 v1, 31, v14
	v_lshrrev_b32_e32 v1, 26, v1
	v_add_u32_e32 v1, v14, v1
	v_ashrrev_i32_e32 v8, 6, v1
	v_bfe_i32 v1, v14, 27, 1
	v_lshlrev_b32_e32 v0, 4, v14
	v_lshrrev_b32_e32 v1, 22, v1
	v_add_u32_e32 v1, v0, v1
	v_and_b32_e32 v1, 0xfffffc00, v1
	v_sub_u32_e32 v1, v0, v1
	v_lshrrev_b32_e32 v2, 4, v1
	v_bitop3_b32 v1, v2, v1, 32 bitop3:0x6c
	v_ashrrev_i32_e32 v3, 31, v1
	v_lshrrev_b32_e32 v3, 26, v3
	v_add_u32_e32 v3, v1, v3
	v_ashrrev_i32_e32 v9, 6, v3
	v_and_b32_e32 v3, 0xc0, v3
	v_sub_u32_e32 v1, v1, v3
	s_lshr_b32 s1, s1, 27
	v_lshlrev_b32_e32 v2, 3, v8
	v_lshlrev_b32_e32 v4, 5, v8
	v_ashrrev_i16_sdwa v1, v133, sext(v1) dst_sel:DWORD dst_unused:UNUSED_PAD src0_sel:DWORD src1_sel:BYTE_0
	s_add_i32 s1, s0, s1
	v_and_b32_e32 v2, 0x1ffff0, v2
	v_and_b32_e32 v4, 32, v4
	v_bfe_i32 v11, v1, 0, 16
	s_ashr_i32 s36, s1, 5
	s_andn2_b32 s1, s1, 31
	v_add_u32_e32 v1, v4, v11
	v_add_lshl_u32 v2, v9, v2, 11
	v_add_u32_e32 v0, 0x2000, v0
	s_sub_i32 s1, s0, s1
	v_lshl_add_u32 v128, v1, 1, v2
	v_ashrrev_i32_e32 v1, 31, v0
	s_ashr_i32 s0, s1, 31
	v_lshrrev_b32_e32 v1, 22, v1
	s_lshr_b32 s0, s0, 29
	v_add_u32_e32 v1, v0, v1
	s_lshl_b32 s20, s36, 3
	s_add_i32 s21, s1, s0
	v_ashrrev_i32_e32 v10, 10, v1
	s_add_i32 s1, s1, s20
	s_and_b32 s37, s21, -8
	v_mul_i32_i24_e32 v1, 0x400, v10
	s_sub_i32 s20, s1, s37
	v_sub_u32_e32 v0, v0, v1
	s_ashr_i32 s0, s21, 3
	s_ashr_i32 s21, s20, 31
	v_lshrrev_b32_e32 v1, 4, v0
	s_lshl_b64 s[22:23], s[20:21], 19
	v_bitop3_b32 v0, v1, v0, 32 bitop3:0x6c
	s_add_u32 s22, s70, s22
	v_readlane_b32 s72, v254, 4
	v_ashrrev_i32_e32 v2, 31, v0
	s_addc_u32 s23, s71, s23
	s_ashr_i32 s1, s0, 31
	v_readlane_b32 s73, v254, 5
	v_lshrrev_b32_e32 v2, 26, v2
	s_lshl_b64 s[24:25], s[0:1], 19
	v_readlane_b32 s74, v254, 6
	v_readlane_b32 s75, v254, 7
	v_readlane_b32 s76, v254, 8
	v_readlane_b32 s77, v254, 9
	s_mov_b64 s[64:65], s[72:73]
	v_add_u32_e32 v2, v0, v2
	s_add_u32 s26, s64, s24
	v_readfirstlane_b32 s1, v14
	v_ashrrev_i32_e32 v12, 6, v2
	v_and_b32_e32 v2, 0xc0, v2
	s_addc_u32 s27, s65, s25
	v_sub_u32_e32 v0, v0, v2
	s_ashr_i32 s35, s1, 6
	v_lshlrev_b32_e32 v1, 3, v10
	v_lshlrev_b32_e32 v3, 5, v10
	v_ashrrev_i16_sdwa v0, v133, sext(v0) dst_sel:DWORD dst_unused:UNUSED_PAD src0_sel:DWORD src1_sel:BYTE_0
	s_lshl_b32 s21, s35, 10
	v_and_b32_e32 v1, 0x1ffff0, v1
	v_and_b32_e32 v3, 32, v3
	v_bfe_i32 v13, v0, 0, 16
	s_add_i32 s29, s21, 0
	v_add_u32_e32 v0, v3, v13
	v_add_lshl_u32 v1, v12, v1, 11
	s_add_i32 m0, s29, 0x10000
	v_lshl_add_u32 v130, v0, 1, v1
	s_add_i32 m0, s29, 0x12000
	s_ashr_i32 s34, s1, 8
	s_mov_b32 m0, s29
	s_add_i32 s30, s29, 0x2000
	s_mov_b32 m0, s30
	s_add_u32 s40, s26, 0x40000
	s_addc_u32 s41, s27, 0
	s_add_i32 m0, s29, 0x14000
	v_mov_b32_e32 v131, v129
	s_add_i32 m0, s29, 0x16000
	v_lshl_add_u64 v[6:7], s[26:27], 0, v[128:129]
	s_add_u32 s40, s22, 0x40000
	s_addc_u32 s41, s23, 0
	s_add_i32 s31, s29, 0x4000
	s_mov_b32 m0, s31
	s_add_i32 s33, s29, 0x6000
	s_mov_b32 m0, s33
	v_lshl_add_u64 v[4:5], s[26:27], 0, v[130:131]
	v_lshl_add_u64 v[2:3], s[22:23], 0, v[128:129]
	s_cmp_lg_u32 s34, 1
	v_lshl_add_u64 v[0:1], s[22:23], 0, v[130:131]
	v_readlane_b32 s78, v254, 10
	v_readlane_b32 s79, v254, 11
	v_readlane_b32 s80, v254, 12
	v_readlane_b32 s81, v254, 13
	v_readlane_b32 s82, v254, 14
	v_readlane_b32 s83, v254, 15
	v_readlane_b32 s84, v254, 16
	v_readlane_b32 s85, v254, 17
	v_readlane_b32 s86, v254, 18
	v_readlane_b32 s87, v254, 19
	s_mov_b64 s[66:67], s[74:75]
	s_mov_b64 s[68:69], s[76:77]
	s_cbranch_scc1 .LBB0_1171
	s_barrier
.LBB0_1171:
	v_and_b32_e32 v15, 15, v14
	v_and_b32_e32 v16, 48, v14
	v_lshlrev_b32_e32 v14, 2, v14
	v_lshlrev_b32_e32 v15, 6, v15
	v_and_b32_e32 v14, 32, v14
	s_lshl_b32 s35, s35, 12
	v_or_b32_e32 v17, v15, v16
	v_bitop3_b32 v15, v15, v14, v16 bitop3:0x36
	s_lshl_b32 s34, s34, 13
	s_and_b32 s35, s35, 0x3000
	s_add_i32 m0, s29, 0x18000
	v_lshl_add_u64 v[6:7], v[6:7], 0, s[6:7]
	v_or_b32_e32 v145, s35, v15
	v_bitop3_b32 v14, v17, s34, v14 bitop3:0xde
	s_waitcnt vmcnt(0)
	s_barrier
	global_load_lds_dwordx4 v[6:7], off
	v_lshl_add_u64 v[4:5], v[4:5], 0, s[6:7]
	s_add_i32 m0, s29, 0x1a000
	s_add_i32 s34, s29, 0x8000
	s_add_i32 s35, s29, 0xa000
	global_load_lds_dwordx4 v[4:5], off
	v_lshl_add_u64 v[2:3], v[2:3], 0, s[6:7]
	s_mov_b32 m0, s34
	s_add_u32 s26, s26, 0x40080
	global_load_lds_dwordx4 v[2:3], off
	v_lshl_add_u64 v[0:1], v[0:1], 0, s[6:7]
	s_mov_b32 m0, s35
	s_addc_u32 s27, s27, 0
	global_load_lds_dwordx4 v[0:1], off
	s_add_i32 m0, s29, 0x1c000
	v_lshl_add_u64 v[0:1], s[26:27], 0, v[128:129]
	global_load_lds_dwordx4 v[0:1], off
	v_lshl_add_u64 v[0:1], s[26:27], 0, v[130:131]
	s_add_i32 m0, s29, 0x1e000
	s_sub_i32 s26, s28, s37
	global_load_lds_dwordx4 v[0:1], off
	s_mul_i32 s36, s36, 24
	s_sub_i32 s26, s26, s36
	s_ashr_i32 s27, s26, 31
	s_lshl_b64 s[26:27], s[26:27], 19
	v_lshlrev_b32_e32 v0, 14, v8
	v_readlane_b32 s72, v254, 4
	v_and_b32_e32 v0, 0xffff8000, v0
	s_add_u32 s26, s70, s26
	v_lshlrev_b32_e32 v2, 14, v10
	v_readlane_b32 s73, v254, 5
	v_lshl_add_u32 v0, v9, 11, v0
	v_and_b32_e32 v1, 1, v8
	s_addc_u32 s27, s71, s27
	v_and_b32_e32 v2, 0xffff8000, v2
	v_readlane_b32 s74, v254, 6
	v_readlane_b32 s75, v254, 7
	v_readlane_b32 s76, v254, 8
	v_readlane_b32 s77, v254, 9
	s_mov_b64 s[64:65], s[72:73]
	v_lshl_or_b32 v0, v1, 6, v0
	v_lshl_add_u32 v2, v12, 11, v2
	v_and_b32_e32 v3, 1, v10
	s_add_u32 s24, s64, s24
	s_waitcnt vmcnt(6)
	v_lshl_add_u32 v0, v11, 1, v0
	v_mov_b32_e32 v1, v129
	v_lshl_or_b32 v2, v3, 6, v2
	s_addc_u32 s25, s65, s25
	v_lshl_add_u64 v[134:135], s[26:27], 0, v[0:1]
	v_lshl_add_u32 v2, v13, 1, v2
	v_mov_b32_e32 v3, v129
	v_lshl_add_u64 v[140:141], s[24:25], 0, v[0:1]
	v_mov_b32_e32 v0, 0
	v_lshl_add_u64 v[138:139], s[26:27], 0, v[2:3]
	v_lshl_add_u64 v[142:143], s[24:25], 0, v[2:3]
	s_mov_b32 s27, -2
	s_mov_b64 s[24:25], 0
	v_add_u32_e32 v146, s42, v145
	v_add_u32_e32 v144, 0, v14
	s_add_i32 s36, s29, 0xc000
	s_add_i32 s26, s29, 0xe000
	v_add_u32_e32 v147, s43, v145
	v_mov_b32_e32 v1, v0
	v_mov_b32_e32 v2, v0
	v_mov_b32_e32 v3, v0
	v_mov_b32_e32 v4, v0
	v_mov_b32_e32 v5, v0
	v_mov_b32_e32 v6, v0
	v_mov_b32_e32 v7, v0
	v_mov_b32_e32 v8, v0
	v_mov_b32_e32 v9, v0
	v_mov_b32_e32 v10, v0
	v_mov_b32_e32 v11, v0
	v_mov_b32_e32 v12, v0
	v_mov_b32_e32 v13, v0
	v_mov_b32_e32 v14, v0
	v_mov_b32_e32 v15, v0
	v_mov_b32_e32 v16, v0
	v_mov_b32_e32 v17, v0
	v_mov_b32_e32 v18, v0
	v_mov_b32_e32 v19, v0
	v_mov_b32_e32 v20, v0
	v_mov_b32_e32 v21, v0
	v_mov_b32_e32 v22, v0
	v_mov_b32_e32 v23, v0
	v_mov_b32_e32 v24, v0
	v_mov_b32_e32 v25, v0
	v_mov_b32_e32 v26, v0
	v_mov_b32_e32 v27, v0
	v_mov_b32_e32 v28, v0
	v_mov_b32_e32 v29, v0
	v_mov_b32_e32 v30, v0
	v_mov_b32_e32 v31, v0
	v_mov_b32_e32 v32, v0
	v_mov_b32_e32 v33, v0
	v_mov_b32_e32 v34, v0
	v_mov_b32_e32 v35, v0
	v_mov_b32_e32 v36, v0
	v_mov_b32_e32 v37, v0
	v_mov_b32_e32 v38, v0
	v_mov_b32_e32 v39, v0
	v_mov_b32_e32 v40, v0
	v_mov_b32_e32 v41, v0
	v_mov_b32_e32 v42, v0
	v_mov_b32_e32 v43, v0
	v_mov_b32_e32 v44, v0
	v_mov_b32_e32 v45, v0
	v_mov_b32_e32 v46, v0
	v_mov_b32_e32 v47, v0
	v_mov_b32_e32 v48, v0
	v_mov_b32_e32 v49, v0
	v_mov_b32_e32 v50, v0
	v_mov_b32_e32 v51, v0
	v_mov_b32_e32 v52, v0
	v_mov_b32_e32 v53, v0
	v_mov_b32_e32 v54, v0
	v_mov_b32_e32 v55, v0
	v_mov_b32_e32 v56, v0
	v_mov_b32_e32 v57, v0
	v_mov_b32_e32 v58, v0
	v_mov_b32_e32 v59, v0
	v_mov_b32_e32 v60, v0
	v_mov_b32_e32 v61, v0
	v_mov_b32_e32 v62, v0
	v_mov_b32_e32 v63, v0
	v_mov_b32_e32 v64, v0
	v_mov_b32_e32 v65, v0
	v_mov_b32_e32 v66, v0
	v_mov_b32_e32 v67, v0
	v_mov_b32_e32 v68, v0
	v_mov_b32_e32 v69, v0
	v_mov_b32_e32 v70, v0
	v_mov_b32_e32 v71, v0
	v_mov_b32_e32 v72, v0
	v_mov_b32_e32 v73, v0
	v_mov_b32_e32 v74, v0
	v_mov_b32_e32 v75, v0
	v_mov_b32_e32 v76, v0
	v_mov_b32_e32 v77, v0
	v_mov_b32_e32 v78, v0
	v_mov_b32_e32 v79, v0
	v_mov_b32_e32 v80, v0
	v_mov_b32_e32 v81, v0
	v_mov_b32_e32 v82, v0
	v_mov_b32_e32 v83, v0
	v_mov_b32_e32 v84, v0
	v_mov_b32_e32 v85, v0
	v_mov_b32_e32 v86, v0
	v_mov_b32_e32 v87, v0
	v_mov_b32_e32 v88, v0
	v_mov_b32_e32 v89, v0
	v_mov_b32_e32 v90, v0
	v_mov_b32_e32 v91, v0
	v_mov_b32_e32 v92, v0
	v_mov_b32_e32 v93, v0
	v_mov_b32_e32 v94, v0
	v_mov_b32_e32 v95, v0
	v_mov_b32_e32 v96, v0
	v_mov_b32_e32 v97, v0
	v_mov_b32_e32 v98, v0
	v_mov_b32_e32 v99, v0
	v_mov_b32_e32 v100, v0
	v_mov_b32_e32 v101, v0
	v_mov_b32_e32 v102, v0
	v_mov_b32_e32 v103, v0
	v_mov_b32_e32 v104, v0
	v_mov_b32_e32 v105, v0
	v_mov_b32_e32 v106, v0
	v_mov_b32_e32 v107, v0
	v_mov_b32_e32 v108, v0
	v_mov_b32_e32 v109, v0
	v_mov_b32_e32 v110, v0
	v_mov_b32_e32 v111, v0
	v_mov_b32_e32 v112, v0
	v_mov_b32_e32 v113, v0
	v_mov_b32_e32 v114, v0
	v_mov_b32_e32 v115, v0
	v_mov_b32_e32 v116, v0
	v_mov_b32_e32 v117, v0
	v_mov_b32_e32 v118, v0
	v_mov_b32_e32 v119, v0
	v_mov_b32_e32 v120, v0
	v_mov_b32_e32 v121, v0
	v_mov_b32_e32 v122, v0
	v_mov_b32_e32 v123, v0
	v_mov_b32_e32 v124, v0
	v_mov_b32_e32 v125, v0
	v_mov_b32_e32 v126, v0
	v_mov_b32_e32 v127, v0
	s_barrier
	v_readlane_b32 s78, v254, 10
	v_readlane_b32 s79, v254, 11
	v_readlane_b32 s80, v254, 12
	v_readlane_b32 s81, v254, 13
	v_readlane_b32 s82, v254, 14
	v_readlane_b32 s83, v254, 15
	v_readlane_b32 s84, v254, 16
	v_readlane_b32 s85, v254, 17
	v_readlane_b32 s86, v254, 18
	v_readlane_b32 s87, v254, 19
	s_mov_b64 s[66:67], s[74:75]
	s_mov_b64 s[68:69], s[76:77]

.LBB0_1384:
	s_or_b64 exec, exec, s[0:1]
	s_and_b64 vcc, exec, s[4:5]
	s_waitcnt lgkmcnt(0)
	s_barrier
	v_lshlrev_b32_e32 v150, 4, v136
	v_and_b32_e32 v151, 0x3ff, v150
	v_lshrrev_b32_e32 v152, 4, v151
	v_and_b32_e32 v152, 32, v152
	v_xor_b32_e32 v151, v151, v152
	v_lshrrev_b32_e32 v152, 10, v150
	v_lshrrev_b32_e32 v153, 1, v152
	v_lshlrev_b32_e32 v153, 4, v153
	v_lshrrev_b32_e32 v150, 6, v151
	v_add_u32_e32 v153, v153, v150
	v_mul_u32_u24_e32 v153, 0x1600, v153
	v_and_b32_e32 v152, 1, v152
	v_lshl_add_u32 v153, v152, 6, v153
	v_and_b32_e32 v151, 63, v151
	v_add_u32_e32 v150, v153, v151
	v_add_u32_e32 v151, 0x58000, v150
	s_and_b32 s72, s2, 7
	s_lshl_b32 s72, s72, 3
	s_bfe_u32 s73, s2, 0x30003
	s_or_b32 s72, s72, s73
	s_mul_i32 s72, s72, 0x160000
	s_add_u32 s74, s66, s72
	s_addc_u32 s75, s67, 0
	v_readlane_b32 s76, v254, 8
	v_readlane_b32 s77, v254, 9
	s_lshr_b32 s72, s2, 6
	s_mul_i32 s72, s72, 0x160000
	s_nop 0
	s_add_u32 s76, s76, s72
	s_addc_u32 s77, s77, 0
	s_add_u32 s78, s76, 0xb0000
	s_addc_u32 s79, s77, 0
	s_add_u32 s80, s74, 0xb0000
	s_addc_u32 s81, s75, 0
	v_readfirstlane_b32 s82, v136
	s_nop 0
	s_lshr_b32 s82, s82, 6
	s_lshl_b32 s82, s82, 10
	s_add_i32 m0, s82, 0x10000
	s_nop 0
	global_load_lds_dwordx4 v150, s[76:77]
	s_add_i32 m0, s82, 0x12000
	s_nop 0
	global_load_lds_dwordx4 v151, s[76:77]
	s_add_i32 m0, s82, 0x0
	s_nop 0
	global_load_lds_dwordx4 v150, s[74:75]
	s_add_i32 m0, s82, 0x2000
	s_nop 0
	global_load_lds_dwordx4 v151, s[74:75]
	s_add_i32 m0, s82, 0x14000
	s_nop 0
	global_load_lds_dwordx4 v150, s[78:79]
	s_add_i32 m0, s82, 0x16000
	s_nop 0
	global_load_lds_dwordx4 v151, s[78:79]
	s_add_i32 m0, s82, 0x4000
	s_nop 0
	global_load_lds_dwordx4 v150, s[80:81]
	s_add_i32 m0, s82, 0x6000
	s_nop 0
	global_load_lds_dwordx4 v151, s[80:81]
	s_cbranch_vccnz .LBB0_1390
	v_readlane_b32 s8, v254, 4
	v_mul_u32_u24_e32 v0, 0x1600, v191
	v_mov_b32_e32 v1, 0
	v_readlane_b32 s12, v254, 8
	v_readlane_b32 s13, v254, 9
	v_mov_b32_e32 v133, v1
	v_mul_u32_u24_e32 v6, 0x160, v187
	v_lshl_add_u64 v[2:3], s[12:13], 0, v[0:1]
	v_lshl_add_u64 v[4:5], v[2:3], 0, v[132:133]
	v_lshl_add_u64 v[2:3], s[66:67], 0, v[0:1]
	v_and_b32_e32 v7, 4, v188
	v_lshl_add_u64 v[2:3], v[2:3], 0, v[132:133]
	v_lshlrev_b32_e32 v0, 1, v6
	v_and_or_b32 v8, v182, 16, v7
	v_readlane_b32 s9, v254, 5
	v_lshl_add_u64 v[2:3], v[2:3], 0, v[0:1]
	v_lshl_add_u64 v[4:5], v[4:5], 0, v[0:1]
	v_lshlrev_b32_e32 v0, 13, v187
	v_lshl_add_u32 v6, v189, 2, 0
	s_movk_i32 s0, 0x100
	v_and_b32_e32 v9, 60, v252
	v_lshlrev_b32_e32 v8, 8, v8
	v_lshl_or_b32 v17, v183, 3, v7
	v_and_b32_e32 v7, 7, v136
	s_mov_b32 s9, 0
	v_cmp_gt_u32_e64 s[0:1], s0, v136
	v_add3_u32 v16, v186, v9, v8
	v_cmp_eq_u32_e64 s[4:5], 0, v7
	s_lshl_b32 s3, s2, 5
	s_lshl_b32 s12, s38, 5
	v_mov_b32_e32 v18, 0x1600
	v_add_u32_e32 v19, v6, v0
	v_lshrrev_b32_e32 v185, 2, v187
	v_lshl_add_u32 v19, v185, 15, v19
	v_add_u32_e32 v19, 0x8000, v19
	v_add_u32_e32 v184, 0x10000, v16
	s_mov_b32 s13, s2
	v_readlane_b32 s10, v254, 6
	v_readlane_b32 s11, v254, 7
	v_readlane_b32 s14, v254, 10
	v_readlane_b32 s15, v254, 11
	v_readlane_b32 s16, v254, 12
	v_readlane_b32 s17, v254, 13
	v_readlane_b32 s18, v254, 14
	v_readlane_b32 s19, v254, 15
	v_readlane_b32 s20, v254, 16
	v_readlane_b32 s21, v254, 17
	v_readlane_b32 s22, v254, 18
	v_readlane_b32 s23, v254, 19
	s_branch .LBB0_1387

.LBB0_1387:
	s_ashr_i32 s14, s13, 6
	s_bfe_u32 s15, s13, 0x20004
	s_and_b32 s17, s3, 0x1e0
	s_lshl_b32 s8, s14, 8
	s_lshl_b32 s10, s15, 5
	s_or_b32 s16, s10, s8
	s_bitset1_b32 s17, 14
	s_waitcnt lgkmcnt(0)
	v_mad_i64_i32 v[6:7], s[10:11], s16, v18, v[4:5]
	s_mul_i32 s8, s17, 0x1600
	global_load_dwordx4 v[20:23], v[6:7], off
	v_lshl_add_u64 v[10:11], v[2:3], 0, s[8:9]
	v_add_co_u32_e32 v8, vcc, 0x16000, v10
	global_load_dwordx4 v[24:27], v[10:11], off
	s_nop 0
	v_addc_co_u32_e32 v9, vcc, 0, v11, vcc
	v_add_co_u32_e32 v14, vcc, 0x16000, v6
	global_load_dwordx4 v[28:31], v[10:11], off offset:64
	global_load_dwordx4 v[32:35], v[6:7], off offset:64
	v_addc_co_u32_e32 v15, vcc, 0, v7, vcc
	global_load_dwordx4 v[36:39], v[14:15], off
	global_load_dwordx4 v[44:47], v[8:9], off
	global_load_dwordx4 v[48:51], v[8:9], off offset:64
	global_load_dwordx4 v[52:55], v[14:15], off offset:64
	v_add_co_u32_e32 v12, vcc, 0xb0000, v6
	s_waitcnt vmcnt(6)
	v_mfma_f32_16x16x32_bf16 v[40:43], v[20:23], v[24:27], 0
	v_addc_co_u32_e32 v13, vcc, 0, v7, vcc
	v_add_co_u32_e32 v96, vcc, 0xc6000, v6
	s_waitcnt vmcnt(2)
	v_mfma_f32_16x16x32_bf16 v[20:23], v[20:23], v[44:47], 0
	v_addc_co_u32_e32 v97, vcc, 0, v7, vcc
	global_load_dwordx4 v[60:63], v[12:13], off
	global_load_dwordx4 v[64:67], v[14:15], off offset:640
	v_mfma_f32_16x16x32_bf16 v[40:43], v[32:35], v[28:31], v[40:43]
	s_waitcnt vmcnt(3)
	v_mfma_f32_16x16x32_bf16 v[20:23], v[32:35], v[48:51], v[20:23]
	global_load_dwordx4 v[32:35], v[96:97], off
	global_load_dwordx4 v[72:75], v[96:97], off offset:64
	v_mfma_f32_16x16x32_bf16 v[56:59], v[36:39], v[24:27], 0
	v_mfma_f32_16x16x32_bf16 v[36:39], v[36:39], v[44:47], 0
	s_waitcnt vmcnt(3)
	v_mfma_f32_16x16x32_bf16 v[68:71], v[60:63], v[24:27], 0
	v_mfma_f32_16x16x32_bf16 v[60:63], v[60:63], v[44:47], 0
	s_waitcnt vmcnt(1)
	v_mfma_f32_16x16x32_bf16 v[24:27], v[32:35], v[24:27], 0
	v_mfma_f32_16x16x32_bf16 v[32:35], v[32:35], v[44:47], 0
	v_mfma_f32_16x16x32_bf16 v[44:47], v[52:55], v[28:31], v[56:59]
	v_mfma_f32_16x16x32_bf16 v[36:39], v[52:55], v[48:51], v[36:39]
	global_load_dwordx4 v[52:55], v[12:13], off offset:64
	s_nop 0
	global_load_dwordx4 v[56:59], v[12:13], off offset:128
	global_load_dwordx4 v[76:79], v[6:7], off offset:128
	s_waitcnt vmcnt(3)
	v_mfma_f32_16x16x32_bf16 v[24:27], v[72:75], v[28:31], v[24:27]
	s_waitcnt vmcnt(2)
	v_mfma_f32_16x16x32_bf16 v[68:71], v[52:55], v[28:31], v[68:71]
	v_mfma_f32_16x16x32_bf16 v[52:55], v[52:55], v[48:51], v[60:63]
	s_nop 2
	global_load_dwordx4 v[60:63], v[10:11], off offset:128
	global_load_dwordx4 v[80:83], v[10:11], off offset:192
	global_load_dwordx4 v[84:87], v[6:7], off offset:192
	global_load_dwordx4 v[88:91], v[8:9], off offset:128
	global_load_dwordx4 v[92:95], v[8:9], off offset:192
	v_mfma_f32_16x16x32_bf16 v[28:31], v[72:75], v[48:51], v[32:35]
	s_nop 2
	global_load_dwordx4 v[32:35], v[14:15], off offset:128
	global_load_dwordx4 v[48:51], v[14:15], off offset:192
	s_waitcnt vmcnt(6)
	v_mfma_f32_16x16x32_bf16 v[40:43], v[76:79], v[60:63], v[40:43]
	s_waitcnt vmcnt(1)
	v_mfma_f32_16x16x32_bf16 v[44:47], v[32:35], v[60:63], v[44:47]
	v_mfma_f32_16x16x32_bf16 v[32:35], v[32:35], v[88:91], v[36:39]
	v_mfma_f32_16x16x32_bf16 v[36:39], v[56:59], v[60:63], v[68:71]
	v_mfma_f32_16x16x32_bf16 v[52:55], v[56:59], v[88:91], v[52:55]
	global_load_dwordx4 v[56:59], v[96:97], off offset:128
	s_nop 0
	global_load_dwordx4 v[68:71], v[96:97], off offset:192
	s_waitcnt vmcnt(2)
	v_mfma_f32_16x16x32_bf16 v[44:47], v[48:51], v[80:83], v[44:47]
	v_mfma_f32_16x16x32_bf16 v[32:35], v[48:51], v[92:95], v[32:35]
	v_mfma_f32_16x16x32_bf16 v[20:23], v[76:79], v[88:91], v[20:23]
	v_mfma_f32_16x16x32_bf16 v[40:43], v[84:87], v[80:83], v[40:43]
	v_mfma_f32_16x16x32_bf16 v[20:23], v[84:87], v[92:95], v[20:23]
	s_waitcnt vmcnt(1)
	v_mfma_f32_16x16x32_bf16 v[24:27], v[56:59], v[60:63], v[24:27]
	v_mfma_f32_16x16x32_bf16 v[28:31], v[56:59], v[88:91], v[28:31]
	global_load_dwordx4 v[48:51], v[12:13], off offset:192
	global_load_dwordx4 v[56:59], v[12:13], off offset:256
	s_waitcnt vmcnt(2)
	v_mfma_f32_16x16x32_bf16 v[24:27], v[68:71], v[80:83], v[24:27]
	v_mfma_f32_16x16x32_bf16 v[28:31], v[68:71], v[92:95], v[28:31]
	s_waitcnt vmcnt(1)
	v_mfma_f32_16x16x32_bf16 v[36:39], v[48:51], v[80:83], v[36:39]
	v_mfma_f32_16x16x32_bf16 v[48:51], v[48:51], v[92:95], v[52:55]
	s_nop 2
	global_load_dwordx4 v[52:55], v[6:7], off offset:256
	global_load_dwordx4 v[60:63], v[10:11], off offset:256
	global_load_dwordx4 v[68:71], v[10:11], off offset:320
	global_load_dwordx4 v[72:75], v[6:7], off offset:320
	global_load_dwordx4 v[76:79], v[8:9], off offset:256
	global_load_dwordx4 v[80:83], v[8:9], off offset:320
	s_waitcnt vmcnt(4)
	v_mfma_f32_16x16x32_bf16 v[36:39], v[56:59], v[60:63], v[36:39]
	v_mfma_f32_16x16x32_bf16 v[40:43], v[52:55], v[60:63], v[40:43]
	s_waitcnt vmcnt(1)
	v_mfma_f32_16x16x32_bf16 v[20:23], v[52:55], v[76:79], v[20:23]
	global_load_dwordx4 v[52:55], v[14:15], off offset:256
	global_load_dwordx4 v[84:87], v[14:15], off offset:320
	v_mfma_f32_16x16x32_bf16 v[48:51], v[56:59], v[76:79], v[48:51]
	s_waitcnt vmcnt(1)
	v_mfma_f32_16x16x32_bf16 v[44:47], v[52:55], v[60:63], v[44:47]
	v_mfma_f32_16x16x32_bf16 v[32:35], v[52:55], v[76:79], v[32:35]
	global_load_dwordx4 v[52:55], v[96:97], off offset:256
	global_load_dwordx4 v[56:59], v[96:97], off offset:320
	s_waitcnt vmcnt(1)
	v_mfma_f32_16x16x32_bf16 v[24:27], v[52:55], v[60:63], v[24:27]
	v_mfma_f32_16x16x32_bf16 v[28:31], v[52:55], v[76:79], v[28:31]
	global_load_dwordx4 v[52:55], v[12:13], off offset:320
	global_load_dwordx4 v[60:63], v[12:13], off offset:384
	s_waitcnt vmcnt(1)
	v_mfma_f32_16x16x32_bf16 v[36:39], v[52:55], v[68:71], v[36:39]
	v_mfma_f32_16x16x32_bf16 v[48:51], v[52:55], v[80:83], v[48:51]
	global_load_dwordx4 v[52:55], v[6:7], off offset:384
	v_mfma_f32_16x16x32_bf16 v[40:43], v[72:75], v[68:71], v[40:43]
	v_mfma_f32_16x16x32_bf16 v[20:23], v[72:75], v[80:83], v[20:23]
	v_mfma_f32_16x16x32_bf16 v[44:47], v[84:87], v[68:71], v[44:47]
	v_mfma_f32_16x16x32_bf16 v[32:35], v[84:87], v[80:83], v[32:35]
	v_mfma_f32_16x16x32_bf16 v[24:27], v[56:59], v[68:71], v[24:27]
	v_mfma_f32_16x16x32_bf16 v[28:31], v[56:59], v[80:83], v[28:31]
	global_load_dwordx4 v[56:59], v[10:11], off offset:384
	global_load_dwordx4 v[68:71], v[10:11], off offset:448
	global_load_dwordx4 v[72:75], v[6:7], off offset:448
	global_load_dwordx4 v[76:79], v[8:9], off offset:384
	global_load_dwordx4 v[80:83], v[8:9], off offset:448
	s_waitcnt vmcnt(4)
	v_mfma_f32_16x16x32_bf16 v[40:43], v[52:55], v[56:59], v[40:43]
	s_waitcnt vmcnt(1)
	v_mfma_f32_16x16x32_bf16 v[20:23], v[52:55], v[76:79], v[20:23]
	global_load_dwordx4 v[52:55], v[14:15], off offset:384
	global_load_dwordx4 v[84:87], v[14:15], off offset:448
	s_waitcnt vmcnt(1)
	v_mfma_f32_16x16x32_bf16 v[44:47], v[52:55], v[56:59], v[44:47]
	v_mfma_f32_16x16x32_bf16 v[32:35], v[52:55], v[76:79], v[32:35]
	v_mfma_f32_16x16x32_bf16 v[36:39], v[60:63], v[56:59], v[36:39]
	v_mfma_f32_16x16x32_bf16 v[48:51], v[60:63], v[76:79], v[48:51]
	global_load_dwordx4 v[52:55], v[96:97], off offset:384
	global_load_dwordx4 v[60:63], v[96:97], off offset:448
	s_waitcnt vmcnt(1)
	v_mfma_f32_16x16x32_bf16 v[24:27], v[52:55], v[56:59], v[24:27]
	v_mfma_f32_16x16x32_bf16 v[28:31], v[52:55], v[76:79], v[28:31]
	global_load_dwordx4 v[52:55], v[12:13], off offset:448
	global_load_dwordx4 v[56:59], v[12:13], off offset:512
	s_waitcnt vmcnt(1)
	v_mfma_f32_16x16x32_bf16 v[36:39], v[52:55], v[68:71], v[36:39]
	v_mfma_f32_16x16x32_bf16 v[48:51], v[52:55], v[80:83], v[48:51]
	global_load_dwordx4 v[52:55], v[6:7], off offset:512
	v_mfma_f32_16x16x32_bf16 v[40:43], v[72:75], v[68:71], v[40:43]
	v_mfma_f32_16x16x32_bf16 v[20:23], v[72:75], v[80:83], v[20:23]
	v_mfma_f32_16x16x32_bf16 v[44:47], v[84:87], v[68:71], v[44:47]
	v_mfma_f32_16x16x32_bf16 v[32:35], v[84:87], v[80:83], v[32:35]
	v_mfma_f32_16x16x32_bf16 v[24:27], v[60:63], v[68:71], v[24:27]
	v_mfma_f32_16x16x32_bf16 v[28:31], v[60:63], v[80:83], v[28:31]
	global_load_dwordx4 v[60:63], v[10:11], off offset:512
	global_load_dwordx4 v[68:71], v[10:11], off offset:576
	global_load_dwordx4 v[72:75], v[6:7], off offset:576
	global_load_dwordx4 v[76:79], v[8:9], off offset:512
	global_load_dwordx4 v[80:83], v[8:9], off offset:576
	s_waitcnt vmcnt(4)
	v_mfma_f32_16x16x32_bf16 v[40:43], v[52:55], v[60:63], v[40:43]
	s_waitcnt vmcnt(1)
	v_mfma_f32_16x16x32_bf16 v[20:23], v[52:55], v[76:79], v[20:23]
	global_load_dwordx4 v[52:55], v[14:15], off offset:512
	global_load_dwordx4 v[84:87], v[14:15], off offset:576
	s_waitcnt vmcnt(1)
	v_mfma_f32_16x16x32_bf16 v[44:47], v[52:55], v[60:63], v[44:47]
	v_mfma_f32_16x16x32_bf16 v[32:35], v[52:55], v[76:79], v[32:35]
	v_mfma_f32_16x16x32_bf16 v[36:39], v[56:59], v[60:63], v[36:39]
	v_mfma_f32_16x16x32_bf16 v[48:51], v[56:59], v[76:79], v[48:51]
	global_load_dwordx4 v[52:55], v[96:97], off offset:512
	global_load_dwordx4 v[56:59], v[96:97], off offset:576
	s_waitcnt vmcnt(1)
	v_mfma_f32_16x16x32_bf16 v[24:27], v[52:55], v[60:63], v[24:27]
	v_mfma_f32_16x16x32_bf16 v[28:31], v[52:55], v[76:79], v[28:31]
	global_load_dwordx4 v[52:55], v[12:13], off offset:576
	global_load_dwordx4 v[60:63], v[12:13], off offset:640
	s_waitcnt vmcnt(1)
	v_mfma_f32_16x16x32_bf16 v[12:15], v[52:55], v[68:71], v[36:39]
	v_mfma_f32_16x16x32_bf16 v[36:39], v[52:55], v[80:83], v[48:51]
	global_load_dwordx4 v[52:55], v[10:11], off offset:640
	s_nop 1
	global_load_dwordx4 v[48:51], v[6:7], off offset:640
	v_mfma_f32_16x16x32_bf16 v[40:43], v[72:75], v[68:71], v[40:43]
	global_load_dwordx4 v[6:9], v[8:9], off offset:640
	v_mfma_f32_16x16x32_bf16 v[20:23], v[72:75], v[80:83], v[20:23]
	s_waitcnt vmcnt(1)
	v_mfma_f32_16x16x32_bf16 v[40:43], v[48:51], v[52:55], v[40:43]
	s_waitcnt vmcnt(0)
	v_mfma_f32_16x16x32_bf16 v[20:23], v[48:51], v[6:9], v[20:23]
	global_load_dwordx4 v[48:51], v[96:97], off offset:640
	s_barrier
	v_mfma_f32_16x16x32_bf16 v[44:47], v[84:87], v[68:71], v[44:47]
	s_nop 2
	ds_write2st64_b32 v19, v40, v41 offset1:1
	ds_write2st64_b32 v19, v42, v43 offset0:2 offset1:3
	v_mfma_f32_16x16x32_bf16 v[24:27], v[56:59], v[68:71], v[24:27]
	v_mfma_f32_16x16x32_bf16 v[32:35], v[84:87], v[80:83], v[32:35]
	v_mfma_f32_16x16x32_bf16 v[44:47], v[64:67], v[52:55], v[44:47]
	v_mfma_f32_16x16x32_bf16 v[10:13], v[60:63], v[52:55], v[12:15]
	s_nop 6
	ds_write2st64_b32 v19, v44, v45 offset0:4 offset1:5
	ds_write2st64_b32 v19, v46, v47 offset0:6 offset1:7
	ds_write2st64_b32 v19, v10, v11 offset0:8 offset1:9
	s_waitcnt vmcnt(0)
	v_mfma_f32_16x16x32_bf16 v[24:27], v[48:51], v[52:55], v[24:27]
	ds_write2st64_b32 v19, v12, v13 offset0:10 offset1:11
	s_nop 6
	ds_write2st64_b32 v19, v24, v25 offset0:12 offset1:13
	ds_write2st64_b32 v19, v26, v27 offset0:14 offset1:15
	v_mfma_f32_16x16x32_bf16 v[28:31], v[56:59], v[80:83], v[28:31]
	v_mfma_f32_16x16x32_bf16 v[10:13], v[64:67], v[6:9], v[32:35]
	ds_write2st64_b32 v19, v20, v21 offset0:16 offset1:17
	ds_write2st64_b32 v19, v22, v23 offset0:18 offset1:19
	s_nop 5
	ds_write2st64_b32 v19, v10, v11 offset0:20 offset1:21
	v_mfma_f32_16x16x32_bf16 v[20:23], v[60:63], v[6:9], v[36:39]
	ds_write2st64_b32 v19, v12, v13 offset0:22 offset1:23
	s_nop 6
	ds_write2st64_b32 v19, v20, v21 offset0:24 offset1:25
	ds_write2st64_b32 v19, v22, v23 offset0:26 offset1:27
	v_mfma_f32_16x16x32_bf16 v[6:9], v[48:51], v[6:9], v[28:31]
	s_nop 7
	ds_write2st64_b32 v19, v6, v7 offset0:28 offset1:29
	ds_write2st64_b32 v19, v8, v9 offset0:30 offset1:31
	s_waitcnt lgkmcnt(0)
	s_barrier
	s_and_saveexec_b64 s[10:11], s[0:1]
	s_cbranch_execz .LBB0_1386
	ds_read2st64_b32 v[6:7], v16 offset0:128 offset1:129
	ds_read2st64_b32 v[8:9], v16 offset0:136 offset1:137
	ds_read2st64_b32 v[10:11], v16 offset0:138 offset1:139
	ds_read2st64_b32 v[12:13], v16 offset0:130 offset1:131
	s_waitcnt lgkmcnt(3)
	v_add_f32_e32 v0, 0, v6
	s_waitcnt lgkmcnt(2)
	v_add_f32_e32 v14, 0, v8
	v_add_f32_e32 v15, 0, v7
	v_add_f32_e32 v20, 0, v9
	ds_read2st64_b32 v[6:7], v16 offset0:160 offset1:161
	ds_read2st64_b32 v[8:9], v16 offset0:168 offset1:169
	s_waitcnt lgkmcnt(2)
	v_add_f32_e32 v21, 0, v12
	v_add_f32_e32 v22, 0, v10
	v_add_f32_e32 v23, 0, v13
	v_add_f32_e32 v24, 0, v11
	ds_read2st64_b32 v[10:11], v16 offset0:170 offset1:171
	ds_read2st64_b32 v[12:13], v16 offset0:162 offset1:163
	s_waitcnt lgkmcnt(3)
	v_add_f32_e32 v0, v0, v6
	s_waitcnt lgkmcnt(2)
	v_add_f32_e32 v14, v14, v8
	v_add_f32_e32 v15, v15, v7
	v_add_f32_e32 v20, v20, v9
	ds_read2st64_b32 v[6:7], v16 offset0:192 offset1:193
	ds_read2st64_b32 v[8:9], v16 offset0:200 offset1:201
	s_waitcnt lgkmcnt(2)
	v_add_f32_e32 v21, v21, v12
	v_add_f32_e32 v22, v22, v10
	v_add_f32_e32 v23, v23, v13
	v_add_f32_e32 v24, v24, v11
	ds_read2st64_b32 v[10:11], v16 offset0:202 offset1:203
	ds_read2st64_b32 v[12:13], v16 offset0:194 offset1:195
	s_waitcnt lgkmcnt(3)
	v_add_f32_e32 v0, v0, v6
	s_waitcnt lgkmcnt(2)
	v_add_f32_e32 v14, v14, v8
	v_add_f32_e32 v15, v15, v7
	v_add_f32_e32 v20, v20, v9
	ds_read2st64_b32 v[6:7], v16 offset0:224 offset1:225
	ds_read2st64_b32 v[8:9], v16 offset0:232 offset1:233
	s_waitcnt lgkmcnt(2)
	v_add_f32_e32 v21, v21, v12
	v_add_f32_e32 v22, v22, v10
	v_add_f32_e32 v23, v23, v13
	v_add_f32_e32 v24, v24, v11
	ds_read2st64_b32 v[10:11], v16 offset0:234 offset1:235
	ds_read2st64_b32 v[12:13], v16 offset0:226 offset1:227
	s_waitcnt lgkmcnt(3)
	v_add_f32_e32 v0, v0, v6
	s_waitcnt lgkmcnt(2)
	v_add_f32_e32 v14, v14, v8
	v_add_f32_e32 v15, v15, v7
	v_add_f32_e32 v20, v20, v9
	ds_read2st64_b32 v[6:7], v184 offset0:128 offset1:129
	ds_read2st64_b32 v[8:9], v184 offset0:136 offset1:137
	s_waitcnt lgkmcnt(2)
	v_add_f32_e32 v21, v21, v12
	v_add_f32_e32 v22, v22, v10
	v_add_f32_e32 v23, v23, v13
	v_add_f32_e32 v24, v24, v11
	ds_read2st64_b32 v[10:11], v184 offset0:138 offset1:139
	ds_read2st64_b32 v[12:13], v184 offset0:130 offset1:131
	s_waitcnt lgkmcnt(3)
	v_add_f32_e32 v0, v0, v6
	s_waitcnt lgkmcnt(2)
	v_add_f32_e32 v14, v14, v8
	v_add_f32_e32 v15, v15, v7
	v_add_f32_e32 v20, v20, v9
	ds_read2st64_b32 v[6:7], v184 offset0:160 offset1:161
	ds_read2st64_b32 v[8:9], v184 offset0:168 offset1:169
	s_waitcnt lgkmcnt(2)
	v_add_f32_e32 v21, v21, v12
	v_add_f32_e32 v22, v22, v10
	v_add_f32_e32 v23, v23, v13
	v_add_f32_e32 v24, v24, v11
	ds_read2st64_b32 v[10:11], v184 offset0:170 offset1:171
	ds_read2st64_b32 v[12:13], v184 offset0:162 offset1:163
	s_waitcnt lgkmcnt(3)
	v_add_f32_e32 v0, v0, v6
	s_waitcnt lgkmcnt(2)
	v_add_f32_e32 v14, v14, v8
	v_add_f32_e32 v15, v15, v7
	v_add_f32_e32 v20, v20, v9
	ds_read2st64_b32 v[6:7], v184 offset0:192 offset1:193
	ds_read2st64_b32 v[8:9], v184 offset0:200 offset1:201
	s_waitcnt lgkmcnt(2)
	v_add_f32_e32 v21, v21, v12
	v_add_f32_e32 v22, v22, v10
	v_add_f32_e32 v23, v23, v13
	v_add_f32_e32 v24, v24, v11
	ds_read2st64_b32 v[10:11], v184 offset0:202 offset1:203
	ds_read2st64_b32 v[12:13], v184 offset0:194 offset1:195
	s_waitcnt lgkmcnt(3)
	v_add_f32_e32 v0, v0, v6
	s_waitcnt lgkmcnt(2)
	v_add_f32_e32 v14, v14, v8
	v_add_f32_e32 v15, v15, v7
	v_add_f32_e32 v20, v20, v9
	ds_read2st64_b32 v[6:7], v184 offset0:224 offset1:225
	ds_read2st64_b32 v[8:9], v184 offset0:232 offset1:233
	s_waitcnt lgkmcnt(2)
	v_add_f32_e32 v21, v21, v12
	v_add_f32_e32 v22, v22, v10
	v_add_f32_e32 v23, v23, v13
	v_add_f32_e32 v24, v24, v11
	ds_read2st64_b32 v[10:11], v184 offset0:234 offset1:235
	ds_read2st64_b32 v[12:13], v184 offset0:226 offset1:227
	s_waitcnt lgkmcnt(3)
	v_add_f32_e32 v7, v15, v7
	s_waitcnt lgkmcnt(2)
	v_add_f32_e32 v15, v20, v9
	v_add_f32_e32 v25, v0, v6
	v_add_f32_e32 v14, v14, v8
	v_mul_f32_e32 v0, v7, v7
	v_mul_f32_e32 v6, v15, v15
	s_waitcnt lgkmcnt(0)
	v_add_f32_e32 v12, v21, v12
	v_add_f32_e32 v20, v22, v10
	v_fmac_f32_e32 v0, v25, v25
	v_fmac_f32_e32 v6, v14, v14
	v_add_f32_e32 v13, v23, v13
	v_add_f32_e32 v21, v24, v11
	v_fmac_f32_e32 v0, v12, v12
	v_fmac_f32_e32 v6, v20, v20
	v_fmac_f32_e32 v0, v13, v13
	v_fmac_f32_e32 v6, v21, v21
	v_add_f32_e32 v9, v0, v6
	v_and_b32_e32 v6, 64, v137
	v_xor_b32_e32 v0, 1, v137
	v_add_u32_e32 v22, 64, v6
	v_cmp_lt_i32_e32 vcc, v0, v22
	v_or_b32_e32 v6, s17, v182
	v_or_b32_e32 v8, s16, v17
	v_cndmask_b32_e32 v0, v137, v0, vcc
	v_lshlrev_b32_e32 v0, 2, v0
	ds_bpermute_b32 v23, v0, v9
	v_lshlrev_b32_e32 v0, 11, v6
	v_lshl_add_u64 v[10:11], s[58:59], 0, v[0:1]
	s_waitcnt lgkmcnt(0)
	v_add_f32_e32 v0, v9, v23
	v_xor_b32_e32 v9, 2, v137
	v_cmp_lt_i32_e32 vcc, v9, v22
	s_nop 1
	v_cndmask_b32_e32 v9, v137, v9, vcc
	v_lshlrev_b32_e32 v9, 2, v9
	ds_bpermute_b32 v23, v9, v0
	v_ashrrev_i32_e32 v9, 31, v8
	v_lshl_add_u64 v[8:9], v[8:9], 1, v[10:11]
	v_cvt_pk_bf16_f32 v10, v25, v7
	v_xor_b32_e32 v7, 4, v137
	v_cmp_lt_i32_e32 vcc, v7, v22
	s_waitcnt lgkmcnt(0)
	v_add_f32_e32 v0, v0, v23
	v_cvt_pk_bf16_f32 v11, v12, v13
	global_store_dwordx2 v[8:9], v[10:11], off
	v_cndmask_b32_e32 v7, v137, v7, vcc
	v_lshlrev_b32_e32 v7, 2, v7
	ds_bpermute_b32 v7, v7, v0
	v_cvt_pk_bf16_f32 v10, v14, v15
	v_cvt_pk_bf16_f32 v11, v20, v21
	global_store_dwordx2 v[8:9], v[10:11], off offset:256
	s_and_b64 exec, exec, s[4:5]
	s_cbranch_execz .LBB0_1386
	s_lshl_b32 s8, s14, 2
	s_or_b32 s8, s8, s15
	s_mul_hi_i32 s15, s8, 0x10800
	s_mul_i32 s8, s8, 0x10800
	s_add_u32 s14, s44, s8
	s_waitcnt lgkmcnt(0)
	v_add_f32_e32 v0, v0, v7
	s_addc_u32 s15, s45, s15
	v_lshlrev_b32_e32 v6, 2, v6
	global_store_dword v6, v0, s[14:15]
	s_branch .LBB0_1386

.LBB0_1393:
	s_lshl_b32 s0, s3, 3
	s_or_b32 s0, s0, s94
	s_mul_i32 s0, s0, s93
	s_add_i32 s0, s0, s95
	s_cmpk_gt_i32 s0, 0xff
	s_cbranch_scc1 .LBB0_1392
	v_mov_b32_e32 v16, v136
	s_waitcnt lgkmcnt(0)
	s_barrier
	s_ashr_i32 s1, s0, 31
	v_ashrrev_i32_e32 v1, 31, v16
	v_lshrrev_b32_e32 v1, 26, v1
	v_add_u32_e32 v1, v16, v1
	v_ashrrev_i32_e32 v8, 6, v1
	v_bfe_i32 v1, v16, 27, 1
	v_lshlrev_b32_e32 v0, 4, v16
	v_lshrrev_b32_e32 v1, 22, v1
	v_add_u32_e32 v1, v0, v1
	v_and_b32_e32 v1, 0xfffffc00, v1
	v_sub_u32_e32 v1, v0, v1
	v_lshrrev_b32_e32 v2, 4, v1
	v_bitop3_b32 v1, v2, v1, 32 bitop3:0x6c
	v_ashrrev_i32_e32 v3, 31, v1
	v_lshrrev_b32_e32 v3, 26, v3
	v_add_u32_e32 v3, v1, v3
	v_lshlrev_b32_e32 v2, 3, v8
	v_ashrrev_i32_e32 v9, 6, v3
	v_and_b32_e32 v3, 0xc0, v3
	v_and_b32_e32 v2, 0xfffff0, v2
	v_sub_u32_e32 v1, v1, v3
	v_add_u32_e32 v2, v9, v2
	v_lshlrev_b32_e32 v4, 5, v8
	v_ashrrev_i16_sdwa v1, v142, sext(v1) dst_sel:DWORD dst_unused:UNUSED_PAD src0_sel:DWORD src1_sel:BYTE_0
	v_and_b32_e32 v10, 32, v4
	v_bfe_i32 v11, v1, 0, 16
	v_mul_lo_u32 v1, v2, s20
	s_lshr_b32 s1, s1, 27
	v_or_b32_e32 v1, v1, v10
	v_add_u32_e32 v0, 0x2000, v0
	s_add_i32 s1, s0, s1
	v_add_lshl_u32 v128, v1, v11, 1
	v_ashrrev_i32_e32 v1, 31, v0
	s_ashr_i32 s35, s1, 5
	s_andn2_b32 s1, s1, 31
	v_lshrrev_b32_e32 v1, 22, v1
	s_sub_i32 s0, s0, s1
	v_add_u32_e32 v1, v0, v1
	s_ashr_i32 s1, s0, 31
	v_ashrrev_i32_e32 v12, 10, v1
	s_lshr_b32 s1, s1, 29
	v_mul_i32_i24_e32 v1, 0x400, v12
	s_lshl_b32 s18, s35, 3
	s_add_i32 s1, s0, s1
	v_sub_u32_e32 v0, v0, v1
	s_add_i32 s0, s0, s18
	s_and_b32 s36, s1, -8
	v_lshrrev_b32_e32 v1, 4, v0
	s_sub_i32 s23, s0, s36
	v_bitop3_b32 v0, v1, v0, 32 bitop3:0x6c
	s_ashr_i32 s22, s1, 3
	s_mul_i32 s0, s23, 0x160000
	v_readlane_b32 s68, v254, 4
	v_ashrrev_i32_e32 v2, 31, v0
	s_mul_hi_i32 s1, s23, 0x160000
	s_add_u32 s0, s66, s0
	v_readlane_b32 s72, v254, 8
	v_readlane_b32 s73, v254, 9
	v_lshrrev_b32_e32 v2, 26, v2
	s_addc_u32 s1, s67, s1
	s_mul_i32 s34, s22, 0x160000
	s_mov_b64 s[40:41], s[72:73]
	v_add_u32_e32 v2, v0, v2
	s_mul_hi_i32 s33, s22, 0x160000
	s_add_u32 s18, s40, s34
	v_readfirstlane_b32 s24, v16
	v_lshlrev_b32_e32 v1, 3, v12
	v_ashrrev_i32_e32 v13, 6, v2
	v_and_b32_e32 v2, 0xc0, v2
	s_addc_u32 s19, s41, s33
	v_and_b32_e32 v1, 0xfffff0, v1
	v_sub_u32_e32 v0, v0, v2
	s_ashr_i32 s31, s24, 6
	v_add_u32_e32 v1, v13, v1
	v_lshlrev_b32_e32 v3, 5, v12
	v_ashrrev_i16_sdwa v0, v142, sext(v0) dst_sel:DWORD dst_unused:UNUSED_PAD src0_sel:DWORD src1_sel:BYTE_0
	s_lshl_b32 s25, s31, 10
	v_and_b32_e32 v14, 32, v3
	v_bfe_i32 v15, v0, 0, 16
	v_mul_lo_u32 v0, v1, s20
	s_add_i32 s26, s25, 0
	v_or_b32_e32 v0, v0, v14
	s_add_i32 m0, s26, 0x10000
	v_add_lshl_u32 v130, v0, v15, 1
	s_add_i32 m0, s26, 0x12000
	s_ashr_i32 s30, s24, 8
	s_mov_b32 m0, s26
	s_add_i32 s27, s26, 0x2000
	s_mov_b32 m0, s27
	s_add_u32 s28, s18, 0xb0000
	s_addc_u32 s29, s19, 0
	s_add_i32 m0, s26, 0x14000
	v_mov_b32_e32 v131, v129
	s_add_i32 m0, s26, 0x16000
	s_add_u32 s40, s0, 0xb0000
	s_addc_u32 s41, s1, 0
	s_add_i32 s28, s26, 0x4000
	s_mov_b32 m0, s28
	s_add_i32 s29, s26, 0x6000
	s_mov_b32 m0, s29
	v_lshl_add_u64 v[6:7], s[18:19], 0, v[128:129]
	v_lshl_add_u64 v[4:5], s[18:19], 0, v[130:131]
	v_lshl_add_u64 v[2:3], s[0:1], 0, v[128:129]
	s_cmp_lg_u32 s30, 1
	v_lshl_add_u64 v[0:1], s[0:1], 0, v[130:131]
	v_readlane_b32 s69, v254, 5
	v_readlane_b32 s70, v254, 6
	v_readlane_b32 s71, v254, 7
	v_readlane_b32 s74, v254, 10
	v_readlane_b32 s75, v254, 11
	v_readlane_b32 s76, v254, 12
	v_readlane_b32 s77, v254, 13
	v_readlane_b32 s78, v254, 14
	v_readlane_b32 s79, v254, 15
	v_readlane_b32 s80, v254, 16
	v_readlane_b32 s81, v254, 17
	v_readlane_b32 s82, v254, 18
	v_readlane_b32 s83, v254, 19
	s_cbranch_scc1 .LBB0_1396
	s_barrier
.LBB0_1396:
	v_and_b32_e32 v17, 15, v16
	v_and_b32_e32 v18, 48, v16
	v_lshlrev_b32_e32 v16, 2, v16
	v_lshlrev_b32_e32 v17, 6, v17
	v_and_b32_e32 v16, 32, v16
	s_lshl_b32 s31, s31, 12
	v_or_b32_e32 v19, v17, v18
	v_bitop3_b32 v17, v17, v16, v18 bitop3:0x36
	s_lshl_b32 s30, s30, 13
	s_and_b32 s31, s31, 0x3000
	s_add_i32 m0, s26, 0x18000
	v_lshl_add_u64 v[6:7], v[6:7], 0, s[4:5]
	v_or_b32_e32 v144, s31, v17
	v_bitop3_b32 v16, v19, s30, v16 bitop3:0xde
	s_waitcnt vmcnt(0)
	s_barrier
	global_load_lds_dwordx4 v[6:7], off
	v_lshl_add_u64 v[4:5], v[4:5], 0, s[4:5]
	s_add_i32 m0, s26, 0x1a000
	s_add_i32 s30, s26, 0x8000
	s_add_i32 s31, s26, 0xa000
	global_load_lds_dwordx4 v[4:5], off
	v_lshl_add_u64 v[2:3], v[2:3], 0, s[4:5]
	s_mov_b32 m0, s30
	s_add_u32 s18, s18, 0xb0080
	global_load_lds_dwordx4 v[2:3], off
	v_lshl_add_u64 v[0:1], v[0:1], 0, s[4:5]
	s_mov_b32 m0, s31
	s_addc_u32 s19, s19, 0
	global_load_lds_dwordx4 v[0:1], off
	s_add_i32 m0, s26, 0x1c000
	v_lshl_add_u64 v[0:1], s[18:19], 0, v[128:129]
	global_load_lds_dwordx4 v[0:1], off
	v_lshl_add_u64 v[0:1], s[18:19], 0, v[130:131]
	s_add_i32 m0, s26, 0x1e000
	s_sub_i32 s18, s96, s36
	global_load_lds_dwordx4 v[0:1], off
	s_mul_i32 s35, s35, 24
	s_sub_i32 s18, s18, s35
	v_lshrrev_b32_e32 v1, 1, v8
	v_mul_lo_u32 v0, v9, s20
	s_mul_hi_i32 s35, s18, 0x160000
	s_mul_i32 s36, s18, 0x160000
	v_mad_u64_u32 v[0:1], s[18:19], v1, s21, v[0:1]
	v_lshrrev_b32_e32 v3, 1, v12
	v_mul_lo_u32 v2, v13, s20
	s_add_u32 s18, s66, s36
	v_mad_u64_u32 v[2:3], s[36:37], v3, s21, v[2:3]
	v_readlane_b32 s68, v254, 4
	v_or_b32_e32 v0, v0, v10
	v_or_b32_e32 v2, v2, v14
	v_readlane_b32 s72, v254, 8
	v_readlane_b32 s73, v254, 9
	v_add_lshl_u32 v0, v0, v11, 1
	v_mov_b32_e32 v1, v129
	s_addc_u32 s19, s67, s35
	v_add_lshl_u32 v2, v2, v15, 1
	v_mov_b32_e32 v3, v129
	s_mov_b64 s[40:41], s[72:73]
	v_lshl_add_u64 v[132:133], s[18:19], 0, v[0:1]
	v_lshl_add_u64 v[134:135], s[18:19], 0, v[2:3]
	s_add_u32 s18, s40, s34
	s_waitcnt vmcnt(6)
	s_addc_u32 s19, s41, s33
	v_lshl_add_u64 v[138:139], s[18:19], 0, v[0:1]
	v_mov_b32_e32 v0, 0
	v_lshl_add_u64 v[140:141], s[18:19], 0, v[2:3]
	s_mov_b32 s33, -2
	s_mov_b64 s[18:19], 0
	v_add_u32_e32 v143, 0, v16
	v_mov_b32_e32 v1, v0
	v_mov_b32_e32 v2, v0
	v_mov_b32_e32 v3, v0
	v_mov_b32_e32 v4, v0
	v_mov_b32_e32 v5, v0
	v_mov_b32_e32 v6, v0
	v_mov_b32_e32 v7, v0
	v_mov_b32_e32 v8, v0
	v_mov_b32_e32 v9, v0
	v_mov_b32_e32 v10, v0
	v_mov_b32_e32 v11, v0
	v_mov_b32_e32 v12, v0
	v_mov_b32_e32 v13, v0
	v_mov_b32_e32 v14, v0
	v_mov_b32_e32 v15, v0
	v_mov_b32_e32 v16, v0
	v_mov_b32_e32 v17, v0
	v_mov_b32_e32 v18, v0
	v_mov_b32_e32 v19, v0
	v_mov_b32_e32 v20, v0
	v_mov_b32_e32 v21, v0
	v_mov_b32_e32 v22, v0
	v_mov_b32_e32 v23, v0
	v_mov_b32_e32 v24, v0
	v_mov_b32_e32 v25, v0
	v_mov_b32_e32 v26, v0
	v_mov_b32_e32 v27, v0
	v_mov_b32_e32 v28, v0
	v_mov_b32_e32 v29, v0
	v_mov_b32_e32 v30, v0
	v_mov_b32_e32 v31, v0
	v_mov_b32_e32 v32, v0
	v_mov_b32_e32 v33, v0
	v_mov_b32_e32 v34, v0
	v_mov_b32_e32 v35, v0
	v_mov_b32_e32 v36, v0
	v_mov_b32_e32 v37, v0
	v_mov_b32_e32 v38, v0
	v_mov_b32_e32 v39, v0
	v_mov_b32_e32 v40, v0
	v_mov_b32_e32 v41, v0
	v_mov_b32_e32 v42, v0
	v_mov_b32_e32 v43, v0
	v_mov_b32_e32 v44, v0
	v_mov_b32_e32 v45, v0
	v_mov_b32_e32 v46, v0
	v_mov_b32_e32 v47, v0
	v_mov_b32_e32 v48, v0
	v_mov_b32_e32 v49, v0
	v_mov_b32_e32 v50, v0
	v_mov_b32_e32 v51, v0
	v_mov_b32_e32 v52, v0
	v_mov_b32_e32 v53, v0
	v_mov_b32_e32 v54, v0
	v_mov_b32_e32 v55, v0
	v_mov_b32_e32 v56, v0
	v_mov_b32_e32 v57, v0
	v_mov_b32_e32 v58, v0
	v_mov_b32_e32 v59, v0
	v_mov_b32_e32 v60, v0
	v_mov_b32_e32 v61, v0
	v_mov_b32_e32 v62, v0
	v_mov_b32_e32 v63, v0
	v_mov_b32_e32 v64, v0
	v_mov_b32_e32 v65, v0
	v_mov_b32_e32 v66, v0
	v_mov_b32_e32 v67, v0
	v_mov_b32_e32 v68, v0
	v_mov_b32_e32 v69, v0
	v_mov_b32_e32 v70, v0
	v_mov_b32_e32 v71, v0
	v_mov_b32_e32 v72, v0
	v_mov_b32_e32 v73, v0
	v_mov_b32_e32 v74, v0
	v_mov_b32_e32 v75, v0
	v_mov_b32_e32 v76, v0
	v_mov_b32_e32 v77, v0
	v_mov_b32_e32 v78, v0
	v_mov_b32_e32 v79, v0
	v_mov_b32_e32 v80, v0
	v_mov_b32_e32 v81, v0
	v_mov_b32_e32 v82, v0
	v_mov_b32_e32 v83, v0
	v_mov_b32_e32 v84, v0
	v_mov_b32_e32 v85, v0
	v_mov_b32_e32 v86, v0
	v_mov_b32_e32 v87, v0
	v_mov_b32_e32 v88, v0
	v_mov_b32_e32 v89, v0
	v_mov_b32_e32 v90, v0
	v_mov_b32_e32 v91, v0
	v_mov_b32_e32 v92, v0
	v_mov_b32_e32 v93, v0
	v_mov_b32_e32 v94, v0
	v_mov_b32_e32 v95, v0
	v_mov_b32_e32 v96, v0
	v_mov_b32_e32 v97, v0
	v_mov_b32_e32 v98, v0
	v_mov_b32_e32 v99, v0
	v_mov_b32_e32 v100, v0
	v_mov_b32_e32 v101, v0
	v_mov_b32_e32 v102, v0
	v_mov_b32_e32 v103, v0
	v_mov_b32_e32 v104, v0
	v_mov_b32_e32 v105, v0
	v_mov_b32_e32 v106, v0
	v_mov_b32_e32 v107, v0
	v_mov_b32_e32 v108, v0
	v_mov_b32_e32 v109, v0
	v_mov_b32_e32 v110, v0
	v_mov_b32_e32 v111, v0
	v_mov_b32_e32 v112, v0
	v_mov_b32_e32 v113, v0
	v_mov_b32_e32 v114, v0
	v_mov_b32_e32 v115, v0
	v_mov_b32_e32 v116, v0
	v_mov_b32_e32 v117, v0
	v_mov_b32_e32 v118, v0
	v_mov_b32_e32 v119, v0
	v_mov_b32_e32 v120, v0
	v_mov_b32_e32 v121, v0
	v_mov_b32_e32 v122, v0
	v_mov_b32_e32 v123, v0
	v_mov_b32_e32 v124, v0
	v_mov_b32_e32 v125, v0
	v_mov_b32_e32 v126, v0
	v_mov_b32_e32 v127, v0
	s_barrier
	v_readlane_b32 s69, v254, 5
	v_readlane_b32 s70, v254, 6
	v_readlane_b32 s71, v254, 7
	v_readlane_b32 s74, v254, 10
	v_readlane_b32 s75, v254, 11
	v_readlane_b32 s76, v254, 12
	v_readlane_b32 s77, v254, 13
	v_readlane_b32 s78, v254, 14
	v_readlane_b32 s79, v254, 15
	v_readlane_b32 s80, v254, 16
	v_readlane_b32 s81, v254, 17
	v_readlane_b32 s82, v254, 18
	v_readlane_b32 s83, v254, 19
